# scanner variant: y-chain interleaved with q-chain after the wait, r loads at end of step (trees kept) + attention combine hoist
# speedup vs baseline: 1.0033x; 1.0033x over previous
; #define LAS __attribute__((address_space(3)))
; __device__ __forceinline__ void rwkv_scan_phase(Frame& F, const bf16* RKV, const float* WAG, const bf16* AGB, const float* k_k, const float* k_a, const float* r_k, bf16* Y, float* BS, float* ST2) {
;     ...
;             for (int ci = 0; ci < SEQ / SC_T; ++ci) {
;                 const LAS unsigned char* bp = F.lds + (ci & 1) * SC_BUF; LAS float* yb = (LAS float*)(F.lds + SC_YOFF + (ci & 1) * SC_YB);
;     ...
;                 f32x2 r0[4], w0[4], k0[4], a0[4], b0[4], r1[4], w1[4], k1[4], a1[4], b1[4]; float v0, v1;
;                 SC_LOAD(r0, w0, k0, a0, b0, v0, 0);
; #pragma unroll
;                 for (int t = 0; t < SC_T; t += 2) {
;                     SC_LOAD(r1, w1, k1, a1, b1, v1, t + 1);
;                     SC_STEP(r0, w0, k0, a0, b0, v0, t);
;                     if (t + 2 < SC_T) SC_LOAD(r0, w0, k0, a0, b0, v0, t + 2);
;                     SC_STEP(r1, w1, k1, a1, b1, v1, t + 1);
;                 }
.LBB0_1692:
	s_and_b32 s6, s0, 1
	s_mul_i32 s7, s6, 0xb000
	s_lshl_b32 s6, s6, 12
	v_add_u32_e32 v74, s7, v91
	v_add_u32_e32 v75, s7, v103
	v_mbcnt_lo_u32_b32 v77, -1, 0
	v_mbcnt_hi_u32_b32 v77, -1, v77
	v_lshlrev_b32_e32 v77, 2, v77
	v_add_u32_e32 v77, 0x18000, v77
	v_cndmask_b32_e64 v76, v77, v170, s[4:5]
	v_add_u32_e32 v76, s6, v76
	ds_read_b128 v[52:55], v74 offset:24576
	ds_read_b128 v[56:59], v74 offset:24592
	ds_read_b128 v[36:39], v74 offset:8192
	ds_read_b128 v[40:43], v74 offset:8208
	ds_read_b128 v[44:47], v74 offset:16384
	ds_read_b128 v[48:51], v74 offset:16400
	ds_read_b128 v[60:63], v74 offset:32768
	ds_read_b128 v[64:67], v74 offset:32784
	ds_read_b32 v68, v75 offset:40960
	ds_read_b128 v[28:31], v74 offset:0
	ds_read_b128 v[32:35], v74 offset:16
	ds_read_b128 v[130:133], v74 offset:24832
	ds_read_b128 v[134:137], v74 offset:24848
	ds_read_b128 v[114:117], v74 offset:8448
	ds_read_b128 v[118:121], v74 offset:8464
	ds_read_b128 v[122:125], v74 offset:16640
	ds_read_b128 v[126:129], v74 offset:16656
	ds_read_b128 v[138:141], v74 offset:33024
	ds_read_b128 v[142:145], v74 offset:33040
	ds_read_b32 v72, v75 offset:41088
	s_waitcnt lgkmcnt(11)
	v_pk_mul_f32 v[0:1], v[8:9], v[52:53]
	v_pk_mul_f32 v[2:3], v[10:11], v[54:55]
	v_pk_fma_f32 v[0:1], v[20:21], v[56:57], v[0:1]
	v_pk_fma_f32 v[2:3], v[22:23], v[58:59], v[2:3]
	v_pk_mul_f32 v[12:13], v[8:9], v[36:37]
	v_pk_mul_f32 v[14:15], v[10:11], v[38:39]
	v_pk_add_f32 v[0:1], v[0:1], v[2:3]
	v_pk_mul_f32 v[16:17], v[20:21], v[40:41]
	v_pk_mul_f32 v[18:19], v[22:23], v[42:43]
	v_add_f32_e32 v24, v0, v1
	v_pk_fma_f32 v[12:13], v[44:45], v[68:69], v[12:13] op_sel_hi:[1,0,1]
	v_pk_fma_f32 v[14:15], v[46:47], v[68:69], v[14:15] op_sel_hi:[1,0,1]
	v_add_f32_dpp v24, v24, v24 quad_perm:[1,0,3,2] row_mask:0xf bank_mask:0xf bound_ctrl:1
	v_pk_fma_f32 v[16:17], v[48:49], v[68:69], v[16:17] op_sel_hi:[1,0,1]
	v_pk_fma_f32 v[18:19], v[50:51], v[68:69], v[18:19] op_sel_hi:[1,0,1]
	v_add_f32_dpp v24, v24, v24 quad_perm:[2,3,0,1] row_mask:0xf bank_mask:0xf bound_ctrl:1
	ds_read_b128 v[106:109], v74 offset:256
	ds_read_b128 v[110:113], v74 offset:272
	v_add_f32_dpp v24, v24, v24 row_half_mirror row_mask:0xf bank_mask:0xf bound_ctrl:1
	v_pk_fma_f32 v[8:9], v[60:61], v[24:25], v[12:13] op_sel_hi:[1,0,1]
	v_pk_fma_f32 v[10:11], v[62:63], v[24:25], v[14:15] op_sel_hi:[1,0,1]
	v_pk_fma_f32 v[20:21], v[64:65], v[24:25], v[16:17] op_sel_hi:[1,0,1]
	v_pk_fma_f32 v[22:23], v[66:67], v[24:25], v[18:19] op_sel_hi:[1,0,1]
	ds_read_b128 v[52:55], v74 offset:25088
	ds_read_b128 v[56:59], v74 offset:25104
	ds_read_b128 v[36:39], v74 offset:8704
	ds_read_b128 v[40:43], v74 offset:8720
	ds_read_b128 v[44:47], v74 offset:16896
	ds_read_b128 v[48:51], v74 offset:16912
	ds_read_b128 v[60:63], v74 offset:33280
	ds_read_b128 v[64:67], v74 offset:33296
	ds_read_b32 v68, v75 offset:41216
	s_waitcnt lgkmcnt(11)
	v_pk_mul_f32 v[0:1], v[8:9], v[130:131]
	v_pk_mul_f32 v[4:5], v[8:9], v[28:29]
	v_pk_mul_f32 v[2:3], v[10:11], v[132:133]
	v_pk_mul_f32 v[6:7], v[10:11], v[30:31]
	v_pk_fma_f32 v[0:1], v[20:21], v[134:135], v[0:1]
	v_pk_fma_f32 v[4:5], v[20:21], v[32:33], v[4:5]
	v_pk_fma_f32 v[2:3], v[22:23], v[136:137], v[2:3]
	v_pk_fma_f32 v[6:7], v[22:23], v[34:35], v[6:7]
	v_pk_mul_f32 v[12:13], v[8:9], v[114:115]
	v_pk_mul_f32 v[14:15], v[10:11], v[116:117]
	v_pk_add_f32 v[0:1], v[0:1], v[2:3]
	v_pk_add_f32 v[4:5], v[4:5], v[6:7]
	v_pk_mul_f32 v[16:17], v[20:21], v[118:119]
	v_pk_mul_f32 v[18:19], v[22:23], v[120:121]
	v_add_f32_e32 v24, v0, v1
	v_add_f32_e32 v26, v4, v5
	v_pk_fma_f32 v[12:13], v[122:123], v[72:73], v[12:13] op_sel_hi:[1,0,1]
	v_pk_fma_f32 v[14:15], v[124:125], v[72:73], v[14:15] op_sel_hi:[1,0,1]
	v_add_f32_dpp v24, v24, v24 quad_perm:[1,0,3,2] row_mask:0xf bank_mask:0xf bound_ctrl:1
	v_add_f32_dpp v26, v26, v26 quad_perm:[1,0,3,2] row_mask:0xf bank_mask:0xf bound_ctrl:1
	v_pk_fma_f32 v[16:17], v[126:127], v[72:73], v[16:17] op_sel_hi:[1,0,1]
	v_pk_fma_f32 v[18:19], v[128:129], v[72:73], v[18:19] op_sel_hi:[1,0,1]
	v_add_f32_dpp v24, v24, v24 quad_perm:[2,3,0,1] row_mask:0xf bank_mask:0xf bound_ctrl:1
	v_add_f32_dpp v26, v26, v26 quad_perm:[2,3,0,1] row_mask:0xf bank_mask:0xf bound_ctrl:1
	ds_read_b128 v[28:31], v74 offset:512
	ds_read_b128 v[32:35], v74 offset:528
	v_add_f32_dpp v24, v24, v24 row_half_mirror row_mask:0xf bank_mask:0xf bound_ctrl:1
	v_add_f32_dpp v26, v26, v26 row_half_mirror row_mask:0xf bank_mask:0xf bound_ctrl:1
	v_pk_fma_f32 v[8:9], v[138:139], v[24:25], v[12:13] op_sel_hi:[1,0,1]
	v_pk_fma_f32 v[10:11], v[140:141], v[24:25], v[14:15] op_sel_hi:[1,0,1]
	v_pk_fma_f32 v[20:21], v[142:143], v[24:25], v[16:17] op_sel_hi:[1,0,1]
	v_pk_fma_f32 v[22:23], v[144:145], v[24:25], v[18:19] op_sel_hi:[1,0,1]
	ds_write_b32 v76, v26 offset:0
	ds_read_b128 v[130:133], v74 offset:25344
	ds_read_b128 v[134:137], v74 offset:25360
	ds_read_b128 v[114:117], v74 offset:8960
	ds_read_b128 v[118:121], v74 offset:8976
	ds_read_b128 v[122:125], v74 offset:17152
	ds_read_b128 v[126:129], v74 offset:17168
	ds_read_b128 v[138:141], v74 offset:33536
	ds_read_b128 v[142:145], v74 offset:33552
	ds_read_b32 v72, v75 offset:41344
	s_waitcnt lgkmcnt(12)
; __device__ __forceinline__ void rwkv_scan_phase(Frame& F, const bf16* RKV, const float* WAG, const bf16* AGB, const float* k_k, const float* k_a, const float* r_k, bf16* Y, float* BS, float* ST2) {
;     ...
;                 f32x2 r0[4], w0[4], k0[4], a0[4], b0[4], r1[4], w1[4], k1[4], a1[4], b1[4]; float v0, v1;
;                 SC_LOAD(r0, w0, k0, a0, b0, v0, 0);
; #pragma unroll
;                 for (int t = 0; t < SC_T; t += 2) {
;                     SC_LOAD(r1, w1, k1, a1, b1, v1, t + 1);
;                     SC_STEP(r0, w0, k0, a0, b0, v0, t);
;                     if (t + 2 < SC_T) SC_LOAD(r0, w0, k0, a0, b0, v0, t + 2);
;                     SC_STEP(r1, w1, k1, a1, b1, v1, t + 1);
	v_pk_mul_f32 v[0:1], v[8:9], v[52:53]
	v_pk_mul_f32 v[4:5], v[8:9], v[106:107]
	v_pk_mul_f32 v[2:3], v[10:11], v[54:55]
	v_pk_mul_f32 v[6:7], v[10:11], v[108:109]
	v_pk_fma_f32 v[0:1], v[20:21], v[56:57], v[0:1]
	v_pk_fma_f32 v[4:5], v[20:21], v[110:111], v[4:5]
	v_pk_fma_f32 v[2:3], v[22:23], v[58:59], v[2:3]
	v_pk_fma_f32 v[6:7], v[22:23], v[112:113], v[6:7]
	v_pk_mul_f32 v[12:13], v[8:9], v[36:37]
	v_pk_mul_f32 v[14:15], v[10:11], v[38:39]
	v_pk_add_f32 v[0:1], v[0:1], v[2:3]
	v_pk_add_f32 v[4:5], v[4:5], v[6:7]
	v_pk_mul_f32 v[16:17], v[20:21], v[40:41]
	v_pk_mul_f32 v[18:19], v[22:23], v[42:43]
	v_add_f32_e32 v24, v0, v1
	v_add_f32_e32 v26, v4, v5
	v_pk_fma_f32 v[12:13], v[44:45], v[68:69], v[12:13] op_sel_hi:[1,0,1]
	v_pk_fma_f32 v[14:15], v[46:47], v[68:69], v[14:15] op_sel_hi:[1,0,1]
	v_add_f32_dpp v24, v24, v24 quad_perm:[1,0,3,2] row_mask:0xf bank_mask:0xf bound_ctrl:1
	v_add_f32_dpp v26, v26, v26 quad_perm:[1,0,3,2] row_mask:0xf bank_mask:0xf bound_ctrl:1
	v_pk_fma_f32 v[16:17], v[48:49], v[68:69], v[16:17] op_sel_hi:[1,0,1]
	v_pk_fma_f32 v[18:19], v[50:51], v[68:69], v[18:19] op_sel_hi:[1,0,1]
	v_add_f32_dpp v24, v24, v24 quad_perm:[2,3,0,1] row_mask:0xf bank_mask:0xf bound_ctrl:1
	v_add_f32_dpp v26, v26, v26 quad_perm:[2,3,0,1] row_mask:0xf bank_mask:0xf bound_ctrl:1
	ds_read_b128 v[106:109], v74 offset:768
	ds_read_b128 v[110:113], v74 offset:784
	v_add_f32_dpp v24, v24, v24 row_half_mirror row_mask:0xf bank_mask:0xf bound_ctrl:1
	v_add_f32_dpp v26, v26, v26 row_half_mirror row_mask:0xf bank_mask:0xf bound_ctrl:1
	v_pk_fma_f32 v[8:9], v[60:61], v[24:25], v[12:13] op_sel_hi:[1,0,1]
	v_pk_fma_f32 v[10:11], v[62:63], v[24:25], v[14:15] op_sel_hi:[1,0,1]
	v_pk_fma_f32 v[20:21], v[64:65], v[24:25], v[16:17] op_sel_hi:[1,0,1]
	v_pk_fma_f32 v[22:23], v[66:67], v[24:25], v[18:19] op_sel_hi:[1,0,1]
	ds_write_b32 v76, v26 offset:128
	ds_read_b128 v[52:55], v74 offset:25600
	ds_read_b128 v[56:59], v74 offset:25616
	ds_read_b128 v[36:39], v74 offset:9216
	ds_read_b128 v[40:43], v74 offset:9232
	ds_read_b128 v[44:47], v74 offset:17408
	ds_read_b128 v[48:51], v74 offset:17424
	ds_read_b128 v[60:63], v74 offset:33792
	ds_read_b128 v[64:67], v74 offset:33808
	ds_read_b32 v68, v75 offset:41472
	s_waitcnt lgkmcnt(12)
	v_pk_mul_f32 v[0:1], v[8:9], v[130:131]
	v_pk_mul_f32 v[4:5], v[8:9], v[28:29]
	v_pk_mul_f32 v[2:3], v[10:11], v[132:133]
	v_pk_mul_f32 v[6:7], v[10:11], v[30:31]
	v_pk_fma_f32 v[0:1], v[20:21], v[134:135], v[0:1]
	v_pk_fma_f32 v[4:5], v[20:21], v[32:33], v[4:5]
	v_pk_fma_f32 v[2:3], v[22:23], v[136:137], v[2:3]
	v_pk_fma_f32 v[6:7], v[22:23], v[34:35], v[6:7]
	v_pk_mul_f32 v[12:13], v[8:9], v[114:115]
	v_pk_mul_f32 v[14:15], v[10:11], v[116:117]
	v_pk_add_f32 v[0:1], v[0:1], v[2:3]
	v_pk_add_f32 v[4:5], v[4:5], v[6:7]
	v_pk_mul_f32 v[16:17], v[20:21], v[118:119]
	v_pk_mul_f32 v[18:19], v[22:23], v[120:121]
	v_add_f32_e32 v24, v0, v1
	v_add_f32_e32 v26, v4, v5
	v_pk_fma_f32 v[12:13], v[122:123], v[72:73], v[12:13] op_sel_hi:[1,0,1]
	v_pk_fma_f32 v[14:15], v[124:125], v[72:73], v[14:15] op_sel_hi:[1,0,1]
	v_add_f32_dpp v24, v24, v24 quad_perm:[1,0,3,2] row_mask:0xf bank_mask:0xf bound_ctrl:1
	v_add_f32_dpp v26, v26, v26 quad_perm:[1,0,3,2] row_mask:0xf bank_mask:0xf bound_ctrl:1
	v_pk_fma_f32 v[16:17], v[126:127], v[72:73], v[16:17] op_sel_hi:[1,0,1]
	v_pk_fma_f32 v[18:19], v[128:129], v[72:73], v[18:19] op_sel_hi:[1,0,1]
	v_add_f32_dpp v24, v24, v24 quad_perm:[2,3,0,1] row_mask:0xf bank_mask:0xf bound_ctrl:1
	v_add_f32_dpp v26, v26, v26 quad_perm:[2,3,0,1] row_mask:0xf bank_mask:0xf bound_ctrl:1
	ds_read_b128 v[28:31], v74 offset:1024
	ds_read_b128 v[32:35], v74 offset:1040
	v_add_f32_dpp v24, v24, v24 row_half_mirror row_mask:0xf bank_mask:0xf bound_ctrl:1
	v_add_f32_dpp v26, v26, v26 row_half_mirror row_mask:0xf bank_mask:0xf bound_ctrl:1
	v_pk_fma_f32 v[8:9], v[138:139], v[24:25], v[12:13] op_sel_hi:[1,0,1]
	v_pk_fma_f32 v[10:11], v[140:141], v[24:25], v[14:15] op_sel_hi:[1,0,1]
	v_pk_fma_f32 v[20:21], v[142:143], v[24:25], v[16:17] op_sel_hi:[1,0,1]
	v_pk_fma_f32 v[22:23], v[144:145], v[24:25], v[18:19] op_sel_hi:[1,0,1]
	ds_write_b32 v76, v26 offset:256
	ds_read_b128 v[130:133], v74 offset:25856
	ds_read_b128 v[134:137], v74 offset:25872
	ds_read_b128 v[114:117], v74 offset:9472
	ds_read_b128 v[118:121], v74 offset:9488
	ds_read_b128 v[122:125], v74 offset:17664
	ds_read_b128 v[126:129], v74 offset:17680
	ds_read_b128 v[138:141], v74 offset:34048
	ds_read_b128 v[142:145], v74 offset:34064
	ds_read_b32 v72, v75 offset:41600
	s_waitcnt lgkmcnt(12)
; __device__ __forceinline__ void rwkv_scan_phase(Frame& F, const bf16* RKV, const float* WAG, const bf16* AGB, const float* k_k, const float* k_a, const float* r_k, bf16* Y, float* BS, float* ST2) {
;     ...
;                 f32x2 r0[4], w0[4], k0[4], a0[4], b0[4], r1[4], w1[4], k1[4], a1[4], b1[4]; float v0, v1;
;                 SC_LOAD(r0, w0, k0, a0, b0, v0, 0);
; #pragma unroll
;                 for (int t = 0; t < SC_T; t += 2) {
;                     SC_LOAD(r1, w1, k1, a1, b1, v1, t + 1);
;                     SC_STEP(r0, w0, k0, a0, b0, v0, t);
;                     if (t + 2 < SC_T) SC_LOAD(r0, w0, k0, a0, b0, v0, t + 2);
;                     SC_STEP(r1, w1, k1, a1, b1, v1, t + 1);
	v_pk_mul_f32 v[0:1], v[8:9], v[52:53]
	v_pk_mul_f32 v[4:5], v[8:9], v[106:107]
	v_pk_mul_f32 v[2:3], v[10:11], v[54:55]
	v_pk_mul_f32 v[6:7], v[10:11], v[108:109]
	v_pk_fma_f32 v[0:1], v[20:21], v[56:57], v[0:1]
	v_pk_fma_f32 v[4:5], v[20:21], v[110:111], v[4:5]
	v_pk_fma_f32 v[2:3], v[22:23], v[58:59], v[2:3]
	v_pk_fma_f32 v[6:7], v[22:23], v[112:113], v[6:7]
	v_pk_mul_f32 v[12:13], v[8:9], v[36:37]
	v_pk_mul_f32 v[14:15], v[10:11], v[38:39]
	v_pk_add_f32 v[0:1], v[0:1], v[2:3]
	v_pk_add_f32 v[4:5], v[4:5], v[6:7]
	v_pk_mul_f32 v[16:17], v[20:21], v[40:41]
	v_pk_mul_f32 v[18:19], v[22:23], v[42:43]
	v_add_f32_e32 v24, v0, v1
	v_add_f32_e32 v26, v4, v5
	v_pk_fma_f32 v[12:13], v[44:45], v[68:69], v[12:13] op_sel_hi:[1,0,1]
	v_pk_fma_f32 v[14:15], v[46:47], v[68:69], v[14:15] op_sel_hi:[1,0,1]
	v_add_f32_dpp v24, v24, v24 quad_perm:[1,0,3,2] row_mask:0xf bank_mask:0xf bound_ctrl:1
	v_add_f32_dpp v26, v26, v26 quad_perm:[1,0,3,2] row_mask:0xf bank_mask:0xf bound_ctrl:1
	v_pk_fma_f32 v[16:17], v[48:49], v[68:69], v[16:17] op_sel_hi:[1,0,1]
	v_pk_fma_f32 v[18:19], v[50:51], v[68:69], v[18:19] op_sel_hi:[1,0,1]
	v_add_f32_dpp v24, v24, v24 quad_perm:[2,3,0,1] row_mask:0xf bank_mask:0xf bound_ctrl:1
	v_add_f32_dpp v26, v26, v26 quad_perm:[2,3,0,1] row_mask:0xf bank_mask:0xf bound_ctrl:1
	ds_read_b128 v[106:109], v74 offset:1280
	ds_read_b128 v[110:113], v74 offset:1296
	v_add_f32_dpp v24, v24, v24 row_half_mirror row_mask:0xf bank_mask:0xf bound_ctrl:1
	v_add_f32_dpp v26, v26, v26 row_half_mirror row_mask:0xf bank_mask:0xf bound_ctrl:1
	v_pk_fma_f32 v[8:9], v[60:61], v[24:25], v[12:13] op_sel_hi:[1,0,1]
	v_pk_fma_f32 v[10:11], v[62:63], v[24:25], v[14:15] op_sel_hi:[1,0,1]
	v_pk_fma_f32 v[20:21], v[64:65], v[24:25], v[16:17] op_sel_hi:[1,0,1]
	v_pk_fma_f32 v[22:23], v[66:67], v[24:25], v[18:19] op_sel_hi:[1,0,1]
	ds_write_b32 v76, v26 offset:384
	ds_read_b128 v[52:55], v74 offset:26112
	ds_read_b128 v[56:59], v74 offset:26128
	ds_read_b128 v[36:39], v74 offset:9728
	ds_read_b128 v[40:43], v74 offset:9744
	ds_read_b128 v[44:47], v74 offset:17920
	ds_read_b128 v[48:51], v74 offset:17936
	ds_read_b128 v[60:63], v74 offset:34304
	ds_read_b128 v[64:67], v74 offset:34320
	ds_read_b32 v68, v75 offset:41728
	s_waitcnt lgkmcnt(12)
	v_pk_mul_f32 v[0:1], v[8:9], v[130:131]
	v_pk_mul_f32 v[4:5], v[8:9], v[28:29]
	v_pk_mul_f32 v[2:3], v[10:11], v[132:133]
	v_pk_mul_f32 v[6:7], v[10:11], v[30:31]
	v_pk_fma_f32 v[0:1], v[20:21], v[134:135], v[0:1]
	v_pk_fma_f32 v[4:5], v[20:21], v[32:33], v[4:5]
	v_pk_fma_f32 v[2:3], v[22:23], v[136:137], v[2:3]
	v_pk_fma_f32 v[6:7], v[22:23], v[34:35], v[6:7]
	v_pk_mul_f32 v[12:13], v[8:9], v[114:115]
	v_pk_mul_f32 v[14:15], v[10:11], v[116:117]
	v_pk_add_f32 v[0:1], v[0:1], v[2:3]
	v_pk_add_f32 v[4:5], v[4:5], v[6:7]
	v_pk_mul_f32 v[16:17], v[20:21], v[118:119]
	v_pk_mul_f32 v[18:19], v[22:23], v[120:121]
	v_add_f32_e32 v24, v0, v1
	v_add_f32_e32 v26, v4, v5
	v_pk_fma_f32 v[12:13], v[122:123], v[72:73], v[12:13] op_sel_hi:[1,0,1]
	v_pk_fma_f32 v[14:15], v[124:125], v[72:73], v[14:15] op_sel_hi:[1,0,1]
	v_add_f32_dpp v24, v24, v24 quad_perm:[1,0,3,2] row_mask:0xf bank_mask:0xf bound_ctrl:1
	v_add_f32_dpp v26, v26, v26 quad_perm:[1,0,3,2] row_mask:0xf bank_mask:0xf bound_ctrl:1
	v_pk_fma_f32 v[16:17], v[126:127], v[72:73], v[16:17] op_sel_hi:[1,0,1]
	v_pk_fma_f32 v[18:19], v[128:129], v[72:73], v[18:19] op_sel_hi:[1,0,1]
	v_add_f32_dpp v24, v24, v24 quad_perm:[2,3,0,1] row_mask:0xf bank_mask:0xf bound_ctrl:1
	v_add_f32_dpp v26, v26, v26 quad_perm:[2,3,0,1] row_mask:0xf bank_mask:0xf bound_ctrl:1
	ds_read_b128 v[28:31], v74 offset:1536
	ds_read_b128 v[32:35], v74 offset:1552
	v_add_f32_dpp v24, v24, v24 row_half_mirror row_mask:0xf bank_mask:0xf bound_ctrl:1
	v_add_f32_dpp v26, v26, v26 row_half_mirror row_mask:0xf bank_mask:0xf bound_ctrl:1
	v_pk_fma_f32 v[8:9], v[138:139], v[24:25], v[12:13] op_sel_hi:[1,0,1]
	v_pk_fma_f32 v[10:11], v[140:141], v[24:25], v[14:15] op_sel_hi:[1,0,1]
	v_pk_fma_f32 v[20:21], v[142:143], v[24:25], v[16:17] op_sel_hi:[1,0,1]
	v_pk_fma_f32 v[22:23], v[144:145], v[24:25], v[18:19] op_sel_hi:[1,0,1]
	ds_write_b32 v76, v26 offset:512
	ds_read_b128 v[130:133], v74 offset:26368
	ds_read_b128 v[134:137], v74 offset:26384
	ds_read_b128 v[114:117], v74 offset:9984
	ds_read_b128 v[118:121], v74 offset:10000
	ds_read_b128 v[122:125], v74 offset:18176
	ds_read_b128 v[126:129], v74 offset:18192
	ds_read_b128 v[138:141], v74 offset:34560
	ds_read_b128 v[142:145], v74 offset:34576
	ds_read_b32 v72, v75 offset:41856
	s_waitcnt lgkmcnt(12)
; __device__ __forceinline__ void rwkv_scan_phase(Frame& F, const bf16* RKV, const float* WAG, const bf16* AGB, const float* k_k, const float* k_a, const float* r_k, bf16* Y, float* BS, float* ST2) {
;     ...
;                 f32x2 r0[4], w0[4], k0[4], a0[4], b0[4], r1[4], w1[4], k1[4], a1[4], b1[4]; float v0, v1;
;                 SC_LOAD(r0, w0, k0, a0, b0, v0, 0);
; #pragma unroll
;                 for (int t = 0; t < SC_T; t += 2) {
;                     SC_LOAD(r1, w1, k1, a1, b1, v1, t + 1);
;                     SC_STEP(r0, w0, k0, a0, b0, v0, t);
;                     if (t + 2 < SC_T) SC_LOAD(r0, w0, k0, a0, b0, v0, t + 2);
;                     SC_STEP(r1, w1, k1, a1, b1, v1, t + 1);
	v_pk_mul_f32 v[0:1], v[8:9], v[52:53]
	v_pk_mul_f32 v[4:5], v[8:9], v[106:107]
	v_pk_mul_f32 v[2:3], v[10:11], v[54:55]
	v_pk_mul_f32 v[6:7], v[10:11], v[108:109]
	v_pk_fma_f32 v[0:1], v[20:21], v[56:57], v[0:1]
	v_pk_fma_f32 v[4:5], v[20:21], v[110:111], v[4:5]
	v_pk_fma_f32 v[2:3], v[22:23], v[58:59], v[2:3]
	v_pk_fma_f32 v[6:7], v[22:23], v[112:113], v[6:7]
	v_pk_mul_f32 v[12:13], v[8:9], v[36:37]
	v_pk_mul_f32 v[14:15], v[10:11], v[38:39]
	v_pk_add_f32 v[0:1], v[0:1], v[2:3]
	v_pk_add_f32 v[4:5], v[4:5], v[6:7]
	v_pk_mul_f32 v[16:17], v[20:21], v[40:41]
	v_pk_mul_f32 v[18:19], v[22:23], v[42:43]
	v_add_f32_e32 v24, v0, v1
	v_add_f32_e32 v26, v4, v5
	v_pk_fma_f32 v[12:13], v[44:45], v[68:69], v[12:13] op_sel_hi:[1,0,1]
	v_pk_fma_f32 v[14:15], v[46:47], v[68:69], v[14:15] op_sel_hi:[1,0,1]
	v_add_f32_dpp v24, v24, v24 quad_perm:[1,0,3,2] row_mask:0xf bank_mask:0xf bound_ctrl:1
	v_add_f32_dpp v26, v26, v26 quad_perm:[1,0,3,2] row_mask:0xf bank_mask:0xf bound_ctrl:1
	v_pk_fma_f32 v[16:17], v[48:49], v[68:69], v[16:17] op_sel_hi:[1,0,1]
	v_pk_fma_f32 v[18:19], v[50:51], v[68:69], v[18:19] op_sel_hi:[1,0,1]
	v_add_f32_dpp v24, v24, v24 quad_perm:[2,3,0,1] row_mask:0xf bank_mask:0xf bound_ctrl:1
	v_add_f32_dpp v26, v26, v26 quad_perm:[2,3,0,1] row_mask:0xf bank_mask:0xf bound_ctrl:1
	ds_read_b128 v[106:109], v74 offset:1792
	ds_read_b128 v[110:113], v74 offset:1808
	v_add_f32_dpp v24, v24, v24 row_half_mirror row_mask:0xf bank_mask:0xf bound_ctrl:1
	v_add_f32_dpp v26, v26, v26 row_half_mirror row_mask:0xf bank_mask:0xf bound_ctrl:1
	v_pk_fma_f32 v[8:9], v[60:61], v[24:25], v[12:13] op_sel_hi:[1,0,1]
	v_pk_fma_f32 v[10:11], v[62:63], v[24:25], v[14:15] op_sel_hi:[1,0,1]
	v_pk_fma_f32 v[20:21], v[64:65], v[24:25], v[16:17] op_sel_hi:[1,0,1]
	v_pk_fma_f32 v[22:23], v[66:67], v[24:25], v[18:19] op_sel_hi:[1,0,1]
	ds_write_b32 v76, v26 offset:640
	ds_read_b128 v[52:55], v74 offset:26624
	ds_read_b128 v[56:59], v74 offset:26640
	ds_read_b128 v[36:39], v74 offset:10240
	ds_read_b128 v[40:43], v74 offset:10256
	ds_read_b128 v[44:47], v74 offset:18432
	ds_read_b128 v[48:51], v74 offset:18448
	ds_read_b128 v[60:63], v74 offset:34816
	ds_read_b128 v[64:67], v74 offset:34832
	ds_read_b32 v68, v75 offset:41984
	s_waitcnt lgkmcnt(12)
	v_pk_mul_f32 v[0:1], v[8:9], v[130:131]
	v_pk_mul_f32 v[4:5], v[8:9], v[28:29]
	v_pk_mul_f32 v[2:3], v[10:11], v[132:133]
	v_pk_mul_f32 v[6:7], v[10:11], v[30:31]
	v_pk_fma_f32 v[0:1], v[20:21], v[134:135], v[0:1]
	v_pk_fma_f32 v[4:5], v[20:21], v[32:33], v[4:5]
	v_pk_fma_f32 v[2:3], v[22:23], v[136:137], v[2:3]
	v_pk_fma_f32 v[6:7], v[22:23], v[34:35], v[6:7]
	v_pk_mul_f32 v[12:13], v[8:9], v[114:115]
	v_pk_mul_f32 v[14:15], v[10:11], v[116:117]
	v_pk_add_f32 v[0:1], v[0:1], v[2:3]
	v_pk_add_f32 v[4:5], v[4:5], v[6:7]
	v_pk_mul_f32 v[16:17], v[20:21], v[118:119]
	v_pk_mul_f32 v[18:19], v[22:23], v[120:121]
	v_add_f32_e32 v24, v0, v1
	v_add_f32_e32 v26, v4, v5
	v_pk_fma_f32 v[12:13], v[122:123], v[72:73], v[12:13] op_sel_hi:[1,0,1]
	v_pk_fma_f32 v[14:15], v[124:125], v[72:73], v[14:15] op_sel_hi:[1,0,1]
	v_add_f32_dpp v24, v24, v24 quad_perm:[1,0,3,2] row_mask:0xf bank_mask:0xf bound_ctrl:1
	v_add_f32_dpp v26, v26, v26 quad_perm:[1,0,3,2] row_mask:0xf bank_mask:0xf bound_ctrl:1
	v_pk_fma_f32 v[16:17], v[126:127], v[72:73], v[16:17] op_sel_hi:[1,0,1]
	v_pk_fma_f32 v[18:19], v[128:129], v[72:73], v[18:19] op_sel_hi:[1,0,1]
	v_add_f32_dpp v24, v24, v24 quad_perm:[2,3,0,1] row_mask:0xf bank_mask:0xf bound_ctrl:1
	v_add_f32_dpp v26, v26, v26 quad_perm:[2,3,0,1] row_mask:0xf bank_mask:0xf bound_ctrl:1
	ds_read_b128 v[28:31], v74 offset:2048
	ds_read_b128 v[32:35], v74 offset:2064
	v_add_f32_dpp v24, v24, v24 row_half_mirror row_mask:0xf bank_mask:0xf bound_ctrl:1
	v_add_f32_dpp v26, v26, v26 row_half_mirror row_mask:0xf bank_mask:0xf bound_ctrl:1
	v_pk_fma_f32 v[8:9], v[138:139], v[24:25], v[12:13] op_sel_hi:[1,0,1]
	v_pk_fma_f32 v[10:11], v[140:141], v[24:25], v[14:15] op_sel_hi:[1,0,1]
	v_pk_fma_f32 v[20:21], v[142:143], v[24:25], v[16:17] op_sel_hi:[1,0,1]
	v_pk_fma_f32 v[22:23], v[144:145], v[24:25], v[18:19] op_sel_hi:[1,0,1]
	ds_write_b32 v76, v26 offset:768
	ds_read_b128 v[130:133], v74 offset:26880
	ds_read_b128 v[134:137], v74 offset:26896
	ds_read_b128 v[114:117], v74 offset:10496
	ds_read_b128 v[118:121], v74 offset:10512
	ds_read_b128 v[122:125], v74 offset:18688
	ds_read_b128 v[126:129], v74 offset:18704
	ds_read_b128 v[138:141], v74 offset:35072
	ds_read_b128 v[142:145], v74 offset:35088
	ds_read_b32 v72, v75 offset:42112
	s_waitcnt lgkmcnt(12)
; __device__ __forceinline__ void rwkv_scan_phase(Frame& F, const bf16* RKV, const float* WAG, const bf16* AGB, const float* k_k, const float* k_a, const float* r_k, bf16* Y, float* BS, float* ST2) {
;     ...
;                 f32x2 r0[4], w0[4], k0[4], a0[4], b0[4], r1[4], w1[4], k1[4], a1[4], b1[4]; float v0, v1;
;                 SC_LOAD(r0, w0, k0, a0, b0, v0, 0);
; #pragma unroll
;                 for (int t = 0; t < SC_T; t += 2) {
;                     SC_LOAD(r1, w1, k1, a1, b1, v1, t + 1);
;                     SC_STEP(r0, w0, k0, a0, b0, v0, t);
;                     if (t + 2 < SC_T) SC_LOAD(r0, w0, k0, a0, b0, v0, t + 2);
;                     SC_STEP(r1, w1, k1, a1, b1, v1, t + 1);
	v_pk_mul_f32 v[0:1], v[8:9], v[52:53]
	v_pk_mul_f32 v[4:5], v[8:9], v[106:107]
	v_pk_mul_f32 v[2:3], v[10:11], v[54:55]
	v_pk_mul_f32 v[6:7], v[10:11], v[108:109]
	v_pk_fma_f32 v[0:1], v[20:21], v[56:57], v[0:1]
	v_pk_fma_f32 v[4:5], v[20:21], v[110:111], v[4:5]
	v_pk_fma_f32 v[2:3], v[22:23], v[58:59], v[2:3]
	v_pk_fma_f32 v[6:7], v[22:23], v[112:113], v[6:7]
	v_pk_mul_f32 v[12:13], v[8:9], v[36:37]
	v_pk_mul_f32 v[14:15], v[10:11], v[38:39]
	v_pk_add_f32 v[0:1], v[0:1], v[2:3]
	v_pk_add_f32 v[4:5], v[4:5], v[6:7]
	v_pk_mul_f32 v[16:17], v[20:21], v[40:41]
	v_pk_mul_f32 v[18:19], v[22:23], v[42:43]
	v_add_f32_e32 v24, v0, v1
	v_add_f32_e32 v26, v4, v5
	v_pk_fma_f32 v[12:13], v[44:45], v[68:69], v[12:13] op_sel_hi:[1,0,1]
	v_pk_fma_f32 v[14:15], v[46:47], v[68:69], v[14:15] op_sel_hi:[1,0,1]
	v_add_f32_dpp v24, v24, v24 quad_perm:[1,0,3,2] row_mask:0xf bank_mask:0xf bound_ctrl:1
	v_add_f32_dpp v26, v26, v26 quad_perm:[1,0,3,2] row_mask:0xf bank_mask:0xf bound_ctrl:1
	v_pk_fma_f32 v[16:17], v[48:49], v[68:69], v[16:17] op_sel_hi:[1,0,1]
	v_pk_fma_f32 v[18:19], v[50:51], v[68:69], v[18:19] op_sel_hi:[1,0,1]
	v_add_f32_dpp v24, v24, v24 quad_perm:[2,3,0,1] row_mask:0xf bank_mask:0xf bound_ctrl:1
	v_add_f32_dpp v26, v26, v26 quad_perm:[2,3,0,1] row_mask:0xf bank_mask:0xf bound_ctrl:1
	ds_read_b128 v[106:109], v74 offset:2304
	ds_read_b128 v[110:113], v74 offset:2320
	v_add_f32_dpp v24, v24, v24 row_half_mirror row_mask:0xf bank_mask:0xf bound_ctrl:1
	v_add_f32_dpp v26, v26, v26 row_half_mirror row_mask:0xf bank_mask:0xf bound_ctrl:1
	v_pk_fma_f32 v[8:9], v[60:61], v[24:25], v[12:13] op_sel_hi:[1,0,1]
	v_pk_fma_f32 v[10:11], v[62:63], v[24:25], v[14:15] op_sel_hi:[1,0,1]
	v_pk_fma_f32 v[20:21], v[64:65], v[24:25], v[16:17] op_sel_hi:[1,0,1]
	v_pk_fma_f32 v[22:23], v[66:67], v[24:25], v[18:19] op_sel_hi:[1,0,1]
	ds_write_b32 v76, v26 offset:896
	ds_read_b128 v[52:55], v74 offset:27136
	ds_read_b128 v[56:59], v74 offset:27152
	ds_read_b128 v[36:39], v74 offset:10752
	ds_read_b128 v[40:43], v74 offset:10768
	ds_read_b128 v[44:47], v74 offset:18944
	ds_read_b128 v[48:51], v74 offset:18960
	ds_read_b128 v[60:63], v74 offset:35328
	ds_read_b128 v[64:67], v74 offset:35344
	ds_read_b32 v68, v75 offset:42240
	s_waitcnt lgkmcnt(12)
	v_pk_mul_f32 v[0:1], v[8:9], v[130:131]
	v_pk_mul_f32 v[4:5], v[8:9], v[28:29]
	v_pk_mul_f32 v[2:3], v[10:11], v[132:133]
	v_pk_mul_f32 v[6:7], v[10:11], v[30:31]
	v_pk_fma_f32 v[0:1], v[20:21], v[134:135], v[0:1]
	v_pk_fma_f32 v[4:5], v[20:21], v[32:33], v[4:5]
	v_pk_fma_f32 v[2:3], v[22:23], v[136:137], v[2:3]
	v_pk_fma_f32 v[6:7], v[22:23], v[34:35], v[6:7]
	v_pk_mul_f32 v[12:13], v[8:9], v[114:115]
	v_pk_mul_f32 v[14:15], v[10:11], v[116:117]
	v_pk_add_f32 v[0:1], v[0:1], v[2:3]
	v_pk_add_f32 v[4:5], v[4:5], v[6:7]
	v_pk_mul_f32 v[16:17], v[20:21], v[118:119]
	v_pk_mul_f32 v[18:19], v[22:23], v[120:121]
	v_add_f32_e32 v24, v0, v1
	v_add_f32_e32 v26, v4, v5
	v_pk_fma_f32 v[12:13], v[122:123], v[72:73], v[12:13] op_sel_hi:[1,0,1]
	v_pk_fma_f32 v[14:15], v[124:125], v[72:73], v[14:15] op_sel_hi:[1,0,1]
	v_add_f32_dpp v24, v24, v24 quad_perm:[1,0,3,2] row_mask:0xf bank_mask:0xf bound_ctrl:1
	v_add_f32_dpp v26, v26, v26 quad_perm:[1,0,3,2] row_mask:0xf bank_mask:0xf bound_ctrl:1
	v_pk_fma_f32 v[16:17], v[126:127], v[72:73], v[16:17] op_sel_hi:[1,0,1]
	v_pk_fma_f32 v[18:19], v[128:129], v[72:73], v[18:19] op_sel_hi:[1,0,1]
	v_add_f32_dpp v24, v24, v24 quad_perm:[2,3,0,1] row_mask:0xf bank_mask:0xf bound_ctrl:1
	v_add_f32_dpp v26, v26, v26 quad_perm:[2,3,0,1] row_mask:0xf bank_mask:0xf bound_ctrl:1
	ds_read_b128 v[28:31], v74 offset:2560
	ds_read_b128 v[32:35], v74 offset:2576
	v_add_f32_dpp v24, v24, v24 row_half_mirror row_mask:0xf bank_mask:0xf bound_ctrl:1
	v_add_f32_dpp v26, v26, v26 row_half_mirror row_mask:0xf bank_mask:0xf bound_ctrl:1
	v_pk_fma_f32 v[8:9], v[138:139], v[24:25], v[12:13] op_sel_hi:[1,0,1]
	v_pk_fma_f32 v[10:11], v[140:141], v[24:25], v[14:15] op_sel_hi:[1,0,1]
	v_pk_fma_f32 v[20:21], v[142:143], v[24:25], v[16:17] op_sel_hi:[1,0,1]
	v_pk_fma_f32 v[22:23], v[144:145], v[24:25], v[18:19] op_sel_hi:[1,0,1]
	ds_write_b32 v76, v26 offset:1024
	ds_read_b128 v[130:133], v74 offset:27392
	ds_read_b128 v[134:137], v74 offset:27408
	ds_read_b128 v[114:117], v74 offset:11008
	ds_read_b128 v[118:121], v74 offset:11024
	ds_read_b128 v[122:125], v74 offset:19200
	ds_read_b128 v[126:129], v74 offset:19216
	ds_read_b128 v[138:141], v74 offset:35584
	ds_read_b128 v[142:145], v74 offset:35600
	ds_read_b32 v72, v75 offset:42368
	s_waitcnt lgkmcnt(12)
; __device__ __forceinline__ void rwkv_scan_phase(Frame& F, const bf16* RKV, const float* WAG, const bf16* AGB, const float* k_k, const float* k_a, const float* r_k, bf16* Y, float* BS, float* ST2) {
;     ...
;                 f32x2 r0[4], w0[4], k0[4], a0[4], b0[4], r1[4], w1[4], k1[4], a1[4], b1[4]; float v0, v1;
;                 SC_LOAD(r0, w0, k0, a0, b0, v0, 0);
; #pragma unroll
;                 for (int t = 0; t < SC_T; t += 2) {
;                     SC_LOAD(r1, w1, k1, a1, b1, v1, t + 1);
;                     SC_STEP(r0, w0, k0, a0, b0, v0, t);
;                     if (t + 2 < SC_T) SC_LOAD(r0, w0, k0, a0, b0, v0, t + 2);
;                     SC_STEP(r1, w1, k1, a1, b1, v1, t + 1);
	v_pk_mul_f32 v[0:1], v[8:9], v[52:53]
	v_pk_mul_f32 v[4:5], v[8:9], v[106:107]
	v_pk_mul_f32 v[2:3], v[10:11], v[54:55]
	v_pk_mul_f32 v[6:7], v[10:11], v[108:109]
	v_pk_fma_f32 v[0:1], v[20:21], v[56:57], v[0:1]
	v_pk_fma_f32 v[4:5], v[20:21], v[110:111], v[4:5]
	v_pk_fma_f32 v[2:3], v[22:23], v[58:59], v[2:3]
	v_pk_fma_f32 v[6:7], v[22:23], v[112:113], v[6:7]
	v_pk_mul_f32 v[12:13], v[8:9], v[36:37]
	v_pk_mul_f32 v[14:15], v[10:11], v[38:39]
	v_pk_add_f32 v[0:1], v[0:1], v[2:3]
	v_pk_add_f32 v[4:5], v[4:5], v[6:7]
	v_pk_mul_f32 v[16:17], v[20:21], v[40:41]
	v_pk_mul_f32 v[18:19], v[22:23], v[42:43]
	v_add_f32_e32 v24, v0, v1
	v_add_f32_e32 v26, v4, v5
	v_pk_fma_f32 v[12:13], v[44:45], v[68:69], v[12:13] op_sel_hi:[1,0,1]
	v_pk_fma_f32 v[14:15], v[46:47], v[68:69], v[14:15] op_sel_hi:[1,0,1]
	v_add_f32_dpp v24, v24, v24 quad_perm:[1,0,3,2] row_mask:0xf bank_mask:0xf bound_ctrl:1
	v_add_f32_dpp v26, v26, v26 quad_perm:[1,0,3,2] row_mask:0xf bank_mask:0xf bound_ctrl:1
	v_pk_fma_f32 v[16:17], v[48:49], v[68:69], v[16:17] op_sel_hi:[1,0,1]
	v_pk_fma_f32 v[18:19], v[50:51], v[68:69], v[18:19] op_sel_hi:[1,0,1]
	v_add_f32_dpp v24, v24, v24 quad_perm:[2,3,0,1] row_mask:0xf bank_mask:0xf bound_ctrl:1
	v_add_f32_dpp v26, v26, v26 quad_perm:[2,3,0,1] row_mask:0xf bank_mask:0xf bound_ctrl:1
	ds_read_b128 v[106:109], v74 offset:2816
	ds_read_b128 v[110:113], v74 offset:2832
	v_add_f32_dpp v24, v24, v24 row_half_mirror row_mask:0xf bank_mask:0xf bound_ctrl:1
	v_add_f32_dpp v26, v26, v26 row_half_mirror row_mask:0xf bank_mask:0xf bound_ctrl:1
	v_pk_fma_f32 v[8:9], v[60:61], v[24:25], v[12:13] op_sel_hi:[1,0,1]
	v_pk_fma_f32 v[10:11], v[62:63], v[24:25], v[14:15] op_sel_hi:[1,0,1]
	v_pk_fma_f32 v[20:21], v[64:65], v[24:25], v[16:17] op_sel_hi:[1,0,1]
	v_pk_fma_f32 v[22:23], v[66:67], v[24:25], v[18:19] op_sel_hi:[1,0,1]
	ds_write_b32 v76, v26 offset:1152
	ds_read_b128 v[52:55], v74 offset:27648
	ds_read_b128 v[56:59], v74 offset:27664
	ds_read_b128 v[36:39], v74 offset:11264
	ds_read_b128 v[40:43], v74 offset:11280
	ds_read_b128 v[44:47], v74 offset:19456
	ds_read_b128 v[48:51], v74 offset:19472
	ds_read_b128 v[60:63], v74 offset:35840
	ds_read_b128 v[64:67], v74 offset:35856
	ds_read_b32 v68, v75 offset:42496
	s_waitcnt lgkmcnt(12)
	v_pk_mul_f32 v[0:1], v[8:9], v[130:131]
	v_pk_mul_f32 v[4:5], v[8:9], v[28:29]
	v_pk_mul_f32 v[2:3], v[10:11], v[132:133]
	v_pk_mul_f32 v[6:7], v[10:11], v[30:31]
	v_pk_fma_f32 v[0:1], v[20:21], v[134:135], v[0:1]
	v_pk_fma_f32 v[4:5], v[20:21], v[32:33], v[4:5]
	v_pk_fma_f32 v[2:3], v[22:23], v[136:137], v[2:3]
	v_pk_fma_f32 v[6:7], v[22:23], v[34:35], v[6:7]
	v_pk_mul_f32 v[12:13], v[8:9], v[114:115]
	v_pk_mul_f32 v[14:15], v[10:11], v[116:117]
	v_pk_add_f32 v[0:1], v[0:1], v[2:3]
	v_pk_add_f32 v[4:5], v[4:5], v[6:7]
	v_pk_mul_f32 v[16:17], v[20:21], v[118:119]
	v_pk_mul_f32 v[18:19], v[22:23], v[120:121]
	v_add_f32_e32 v24, v0, v1
	v_add_f32_e32 v26, v4, v5
	v_pk_fma_f32 v[12:13], v[122:123], v[72:73], v[12:13] op_sel_hi:[1,0,1]
	v_pk_fma_f32 v[14:15], v[124:125], v[72:73], v[14:15] op_sel_hi:[1,0,1]
	v_add_f32_dpp v24, v24, v24 quad_perm:[1,0,3,2] row_mask:0xf bank_mask:0xf bound_ctrl:1
	v_add_f32_dpp v26, v26, v26 quad_perm:[1,0,3,2] row_mask:0xf bank_mask:0xf bound_ctrl:1
	v_pk_fma_f32 v[16:17], v[126:127], v[72:73], v[16:17] op_sel_hi:[1,0,1]
	v_pk_fma_f32 v[18:19], v[128:129], v[72:73], v[18:19] op_sel_hi:[1,0,1]
	v_add_f32_dpp v24, v24, v24 quad_perm:[2,3,0,1] row_mask:0xf bank_mask:0xf bound_ctrl:1
	v_add_f32_dpp v26, v26, v26 quad_perm:[2,3,0,1] row_mask:0xf bank_mask:0xf bound_ctrl:1
	ds_read_b128 v[28:31], v74 offset:3072
	ds_read_b128 v[32:35], v74 offset:3088
	v_add_f32_dpp v24, v24, v24 row_half_mirror row_mask:0xf bank_mask:0xf bound_ctrl:1
	v_add_f32_dpp v26, v26, v26 row_half_mirror row_mask:0xf bank_mask:0xf bound_ctrl:1
	v_pk_fma_f32 v[8:9], v[138:139], v[24:25], v[12:13] op_sel_hi:[1,0,1]
	v_pk_fma_f32 v[10:11], v[140:141], v[24:25], v[14:15] op_sel_hi:[1,0,1]
	v_pk_fma_f32 v[20:21], v[142:143], v[24:25], v[16:17] op_sel_hi:[1,0,1]
	v_pk_fma_f32 v[22:23], v[144:145], v[24:25], v[18:19] op_sel_hi:[1,0,1]
	ds_write_b32 v76, v26 offset:1280
	ds_read_b128 v[130:133], v74 offset:27904
	ds_read_b128 v[134:137], v74 offset:27920
	ds_read_b128 v[114:117], v74 offset:11520
	ds_read_b128 v[118:121], v74 offset:11536
	ds_read_b128 v[122:125], v74 offset:19712
	ds_read_b128 v[126:129], v74 offset:19728
	ds_read_b128 v[138:141], v74 offset:36096
	ds_read_b128 v[142:145], v74 offset:36112
	ds_read_b32 v72, v75 offset:42624
	s_waitcnt lgkmcnt(12)
; __device__ __forceinline__ void rwkv_scan_phase(Frame& F, const bf16* RKV, const float* WAG, const bf16* AGB, const float* k_k, const float* k_a, const float* r_k, bf16* Y, float* BS, float* ST2) {
;     ...
;                 f32x2 r0[4], w0[4], k0[4], a0[4], b0[4], r1[4], w1[4], k1[4], a1[4], b1[4]; float v0, v1;
;                 SC_LOAD(r0, w0, k0, a0, b0, v0, 0);
; #pragma unroll
;                 for (int t = 0; t < SC_T; t += 2) {
;                     SC_LOAD(r1, w1, k1, a1, b1, v1, t + 1);
;                     SC_STEP(r0, w0, k0, a0, b0, v0, t);
;                     if (t + 2 < SC_T) SC_LOAD(r0, w0, k0, a0, b0, v0, t + 2);
;                     SC_STEP(r1, w1, k1, a1, b1, v1, t + 1);
	v_pk_mul_f32 v[0:1], v[8:9], v[52:53]
	v_pk_mul_f32 v[4:5], v[8:9], v[106:107]
	v_pk_mul_f32 v[2:3], v[10:11], v[54:55]
	v_pk_mul_f32 v[6:7], v[10:11], v[108:109]
	v_pk_fma_f32 v[0:1], v[20:21], v[56:57], v[0:1]
	v_pk_fma_f32 v[4:5], v[20:21], v[110:111], v[4:5]
	v_pk_fma_f32 v[2:3], v[22:23], v[58:59], v[2:3]
	v_pk_fma_f32 v[6:7], v[22:23], v[112:113], v[6:7]
	v_pk_mul_f32 v[12:13], v[8:9], v[36:37]
	v_pk_mul_f32 v[14:15], v[10:11], v[38:39]
	v_pk_add_f32 v[0:1], v[0:1], v[2:3]
	v_pk_add_f32 v[4:5], v[4:5], v[6:7]
	v_pk_mul_f32 v[16:17], v[20:21], v[40:41]
	v_pk_mul_f32 v[18:19], v[22:23], v[42:43]
	v_add_f32_e32 v24, v0, v1
	v_add_f32_e32 v26, v4, v5
	v_pk_fma_f32 v[12:13], v[44:45], v[68:69], v[12:13] op_sel_hi:[1,0,1]
	v_pk_fma_f32 v[14:15], v[46:47], v[68:69], v[14:15] op_sel_hi:[1,0,1]
	v_add_f32_dpp v24, v24, v24 quad_perm:[1,0,3,2] row_mask:0xf bank_mask:0xf bound_ctrl:1
	v_add_f32_dpp v26, v26, v26 quad_perm:[1,0,3,2] row_mask:0xf bank_mask:0xf bound_ctrl:1
	v_pk_fma_f32 v[16:17], v[48:49], v[68:69], v[16:17] op_sel_hi:[1,0,1]
	v_pk_fma_f32 v[18:19], v[50:51], v[68:69], v[18:19] op_sel_hi:[1,0,1]
	v_add_f32_dpp v24, v24, v24 quad_perm:[2,3,0,1] row_mask:0xf bank_mask:0xf bound_ctrl:1
	v_add_f32_dpp v26, v26, v26 quad_perm:[2,3,0,1] row_mask:0xf bank_mask:0xf bound_ctrl:1
	ds_read_b128 v[106:109], v74 offset:3328
	ds_read_b128 v[110:113], v74 offset:3344
	v_add_f32_dpp v24, v24, v24 row_half_mirror row_mask:0xf bank_mask:0xf bound_ctrl:1
	v_add_f32_dpp v26, v26, v26 row_half_mirror row_mask:0xf bank_mask:0xf bound_ctrl:1
	v_pk_fma_f32 v[8:9], v[60:61], v[24:25], v[12:13] op_sel_hi:[1,0,1]
	v_pk_fma_f32 v[10:11], v[62:63], v[24:25], v[14:15] op_sel_hi:[1,0,1]
	v_pk_fma_f32 v[20:21], v[64:65], v[24:25], v[16:17] op_sel_hi:[1,0,1]
	v_pk_fma_f32 v[22:23], v[66:67], v[24:25], v[18:19] op_sel_hi:[1,0,1]
	ds_write_b32 v76, v26 offset:1408
	ds_read_b128 v[52:55], v74 offset:28160
	ds_read_b128 v[56:59], v74 offset:28176
	ds_read_b128 v[36:39], v74 offset:11776
	ds_read_b128 v[40:43], v74 offset:11792
	ds_read_b128 v[44:47], v74 offset:19968
	ds_read_b128 v[48:51], v74 offset:19984
	ds_read_b128 v[60:63], v74 offset:36352
	ds_read_b128 v[64:67], v74 offset:36368
	ds_read_b32 v68, v75 offset:42752
	s_waitcnt lgkmcnt(12)
	v_pk_mul_f32 v[0:1], v[8:9], v[130:131]
	v_pk_mul_f32 v[4:5], v[8:9], v[28:29]
	v_pk_mul_f32 v[2:3], v[10:11], v[132:133]
	v_pk_mul_f32 v[6:7], v[10:11], v[30:31]
	v_pk_fma_f32 v[0:1], v[20:21], v[134:135], v[0:1]
	v_pk_fma_f32 v[4:5], v[20:21], v[32:33], v[4:5]
	v_pk_fma_f32 v[2:3], v[22:23], v[136:137], v[2:3]
	v_pk_fma_f32 v[6:7], v[22:23], v[34:35], v[6:7]
	v_pk_mul_f32 v[12:13], v[8:9], v[114:115]
	v_pk_mul_f32 v[14:15], v[10:11], v[116:117]
	v_pk_add_f32 v[0:1], v[0:1], v[2:3]
	v_pk_add_f32 v[4:5], v[4:5], v[6:7]
	v_pk_mul_f32 v[16:17], v[20:21], v[118:119]
	v_pk_mul_f32 v[18:19], v[22:23], v[120:121]
	v_add_f32_e32 v24, v0, v1
	v_add_f32_e32 v26, v4, v5
	v_pk_fma_f32 v[12:13], v[122:123], v[72:73], v[12:13] op_sel_hi:[1,0,1]
	v_pk_fma_f32 v[14:15], v[124:125], v[72:73], v[14:15] op_sel_hi:[1,0,1]
	v_add_f32_dpp v24, v24, v24 quad_perm:[1,0,3,2] row_mask:0xf bank_mask:0xf bound_ctrl:1
	v_add_f32_dpp v26, v26, v26 quad_perm:[1,0,3,2] row_mask:0xf bank_mask:0xf bound_ctrl:1
	v_pk_fma_f32 v[16:17], v[126:127], v[72:73], v[16:17] op_sel_hi:[1,0,1]
	v_pk_fma_f32 v[18:19], v[128:129], v[72:73], v[18:19] op_sel_hi:[1,0,1]
	v_add_f32_dpp v24, v24, v24 quad_perm:[2,3,0,1] row_mask:0xf bank_mask:0xf bound_ctrl:1
	v_add_f32_dpp v26, v26, v26 quad_perm:[2,3,0,1] row_mask:0xf bank_mask:0xf bound_ctrl:1
	ds_read_b128 v[28:31], v74 offset:3584
	ds_read_b128 v[32:35], v74 offset:3600
	v_add_f32_dpp v24, v24, v24 row_half_mirror row_mask:0xf bank_mask:0xf bound_ctrl:1
	v_add_f32_dpp v26, v26, v26 row_half_mirror row_mask:0xf bank_mask:0xf bound_ctrl:1
	v_pk_fma_f32 v[8:9], v[138:139], v[24:25], v[12:13] op_sel_hi:[1,0,1]
	v_pk_fma_f32 v[10:11], v[140:141], v[24:25], v[14:15] op_sel_hi:[1,0,1]
	v_pk_fma_f32 v[20:21], v[142:143], v[24:25], v[16:17] op_sel_hi:[1,0,1]
	v_pk_fma_f32 v[22:23], v[144:145], v[24:25], v[18:19] op_sel_hi:[1,0,1]
	ds_write_b32 v76, v26 offset:1536
	ds_read_b128 v[130:133], v74 offset:28416
	ds_read_b128 v[134:137], v74 offset:28432
	ds_read_b128 v[114:117], v74 offset:12032
	ds_read_b128 v[118:121], v74 offset:12048
	ds_read_b128 v[122:125], v74 offset:20224
	ds_read_b128 v[126:129], v74 offset:20240
	ds_read_b128 v[138:141], v74 offset:36608
	ds_read_b128 v[142:145], v74 offset:36624
	ds_read_b32 v72, v75 offset:42880
	s_waitcnt lgkmcnt(12)
; __device__ __forceinline__ void rwkv_scan_phase(Frame& F, const bf16* RKV, const float* WAG, const bf16* AGB, const float* k_k, const float* k_a, const float* r_k, bf16* Y, float* BS, float* ST2) {
;     ...
;                 f32x2 r0[4], w0[4], k0[4], a0[4], b0[4], r1[4], w1[4], k1[4], a1[4], b1[4]; float v0, v1;
;                 SC_LOAD(r0, w0, k0, a0, b0, v0, 0);
; #pragma unroll
;                 for (int t = 0; t < SC_T; t += 2) {
;                     SC_LOAD(r1, w1, k1, a1, b1, v1, t + 1);
;                     SC_STEP(r0, w0, k0, a0, b0, v0, t);
;                     if (t + 2 < SC_T) SC_LOAD(r0, w0, k0, a0, b0, v0, t + 2);
;                     SC_STEP(r1, w1, k1, a1, b1, v1, t + 1);
	v_pk_mul_f32 v[0:1], v[8:9], v[52:53]
	v_pk_mul_f32 v[4:5], v[8:9], v[106:107]
	v_pk_mul_f32 v[2:3], v[10:11], v[54:55]
	v_pk_mul_f32 v[6:7], v[10:11], v[108:109]
	v_pk_fma_f32 v[0:1], v[20:21], v[56:57], v[0:1]
	v_pk_fma_f32 v[4:5], v[20:21], v[110:111], v[4:5]
	v_pk_fma_f32 v[2:3], v[22:23], v[58:59], v[2:3]
	v_pk_fma_f32 v[6:7], v[22:23], v[112:113], v[6:7]
	v_pk_mul_f32 v[12:13], v[8:9], v[36:37]
	v_pk_mul_f32 v[14:15], v[10:11], v[38:39]
	v_pk_add_f32 v[0:1], v[0:1], v[2:3]
	v_pk_add_f32 v[4:5], v[4:5], v[6:7]
	v_pk_mul_f32 v[16:17], v[20:21], v[40:41]
	v_pk_mul_f32 v[18:19], v[22:23], v[42:43]
	v_add_f32_e32 v24, v0, v1
	v_add_f32_e32 v26, v4, v5
	v_pk_fma_f32 v[12:13], v[44:45], v[68:69], v[12:13] op_sel_hi:[1,0,1]
	v_pk_fma_f32 v[14:15], v[46:47], v[68:69], v[14:15] op_sel_hi:[1,0,1]
	v_add_f32_dpp v24, v24, v24 quad_perm:[1,0,3,2] row_mask:0xf bank_mask:0xf bound_ctrl:1
	v_add_f32_dpp v26, v26, v26 quad_perm:[1,0,3,2] row_mask:0xf bank_mask:0xf bound_ctrl:1
	v_pk_fma_f32 v[16:17], v[48:49], v[68:69], v[16:17] op_sel_hi:[1,0,1]
	v_pk_fma_f32 v[18:19], v[50:51], v[68:69], v[18:19] op_sel_hi:[1,0,1]
	v_add_f32_dpp v24, v24, v24 quad_perm:[2,3,0,1] row_mask:0xf bank_mask:0xf bound_ctrl:1
	v_add_f32_dpp v26, v26, v26 quad_perm:[2,3,0,1] row_mask:0xf bank_mask:0xf bound_ctrl:1
	ds_read_b128 v[106:109], v74 offset:3840
	ds_read_b128 v[110:113], v74 offset:3856
	v_add_f32_dpp v24, v24, v24 row_half_mirror row_mask:0xf bank_mask:0xf bound_ctrl:1
	v_add_f32_dpp v26, v26, v26 row_half_mirror row_mask:0xf bank_mask:0xf bound_ctrl:1
	v_pk_fma_f32 v[8:9], v[60:61], v[24:25], v[12:13] op_sel_hi:[1,0,1]
	v_pk_fma_f32 v[10:11], v[62:63], v[24:25], v[14:15] op_sel_hi:[1,0,1]
	v_pk_fma_f32 v[20:21], v[64:65], v[24:25], v[16:17] op_sel_hi:[1,0,1]
	v_pk_fma_f32 v[22:23], v[66:67], v[24:25], v[18:19] op_sel_hi:[1,0,1]
	ds_write_b32 v76, v26 offset:1664
	ds_read_b128 v[52:55], v74 offset:28672
	ds_read_b128 v[56:59], v74 offset:28688
	ds_read_b128 v[36:39], v74 offset:12288
	ds_read_b128 v[40:43], v74 offset:12304
	ds_read_b128 v[44:47], v74 offset:20480
	ds_read_b128 v[48:51], v74 offset:20496
	ds_read_b128 v[60:63], v74 offset:36864
	ds_read_b128 v[64:67], v74 offset:36880
	ds_read_b32 v68, v75 offset:43008
	s_waitcnt lgkmcnt(12)
	v_pk_mul_f32 v[0:1], v[8:9], v[130:131]
	v_pk_mul_f32 v[4:5], v[8:9], v[28:29]
	v_pk_mul_f32 v[2:3], v[10:11], v[132:133]
	v_pk_mul_f32 v[6:7], v[10:11], v[30:31]
	v_pk_fma_f32 v[0:1], v[20:21], v[134:135], v[0:1]
	v_pk_fma_f32 v[4:5], v[20:21], v[32:33], v[4:5]
	v_pk_fma_f32 v[2:3], v[22:23], v[136:137], v[2:3]
	v_pk_fma_f32 v[6:7], v[22:23], v[34:35], v[6:7]
	v_pk_mul_f32 v[12:13], v[8:9], v[114:115]
	v_pk_mul_f32 v[14:15], v[10:11], v[116:117]
	v_pk_add_f32 v[0:1], v[0:1], v[2:3]
	v_pk_add_f32 v[4:5], v[4:5], v[6:7]
	v_pk_mul_f32 v[16:17], v[20:21], v[118:119]
	v_pk_mul_f32 v[18:19], v[22:23], v[120:121]
	v_add_f32_e32 v24, v0, v1
	v_add_f32_e32 v26, v4, v5
	v_pk_fma_f32 v[12:13], v[122:123], v[72:73], v[12:13] op_sel_hi:[1,0,1]
	v_pk_fma_f32 v[14:15], v[124:125], v[72:73], v[14:15] op_sel_hi:[1,0,1]
	v_add_f32_dpp v24, v24, v24 quad_perm:[1,0,3,2] row_mask:0xf bank_mask:0xf bound_ctrl:1
	v_add_f32_dpp v26, v26, v26 quad_perm:[1,0,3,2] row_mask:0xf bank_mask:0xf bound_ctrl:1
	v_pk_fma_f32 v[16:17], v[126:127], v[72:73], v[16:17] op_sel_hi:[1,0,1]
	v_pk_fma_f32 v[18:19], v[128:129], v[72:73], v[18:19] op_sel_hi:[1,0,1]
	v_add_f32_dpp v24, v24, v24 quad_perm:[2,3,0,1] row_mask:0xf bank_mask:0xf bound_ctrl:1
	v_add_f32_dpp v26, v26, v26 quad_perm:[2,3,0,1] row_mask:0xf bank_mask:0xf bound_ctrl:1
	ds_read_b128 v[28:31], v74 offset:4096
	ds_read_b128 v[32:35], v74 offset:4112
	v_add_f32_dpp v24, v24, v24 row_half_mirror row_mask:0xf bank_mask:0xf bound_ctrl:1
	v_add_f32_dpp v26, v26, v26 row_half_mirror row_mask:0xf bank_mask:0xf bound_ctrl:1
	v_pk_fma_f32 v[8:9], v[138:139], v[24:25], v[12:13] op_sel_hi:[1,0,1]
	v_pk_fma_f32 v[10:11], v[140:141], v[24:25], v[14:15] op_sel_hi:[1,0,1]
	v_pk_fma_f32 v[20:21], v[142:143], v[24:25], v[16:17] op_sel_hi:[1,0,1]
	v_pk_fma_f32 v[22:23], v[144:145], v[24:25], v[18:19] op_sel_hi:[1,0,1]
	ds_write_b32 v76, v26 offset:1792
	ds_read_b128 v[130:133], v74 offset:28928
	ds_read_b128 v[134:137], v74 offset:28944
	ds_read_b128 v[114:117], v74 offset:12544
	ds_read_b128 v[118:121], v74 offset:12560
	ds_read_b128 v[122:125], v74 offset:20736
	ds_read_b128 v[126:129], v74 offset:20752
	ds_read_b128 v[138:141], v74 offset:37120
	ds_read_b128 v[142:145], v74 offset:37136
	ds_read_b32 v72, v75 offset:43136
	s_waitcnt lgkmcnt(12)
; __device__ __forceinline__ void rwkv_scan_phase(Frame& F, const bf16* RKV, const float* WAG, const bf16* AGB, const float* k_k, const float* k_a, const float* r_k, bf16* Y, float* BS, float* ST2) {
;     ...
;                 f32x2 r0[4], w0[4], k0[4], a0[4], b0[4], r1[4], w1[4], k1[4], a1[4], b1[4]; float v0, v1;
;                 SC_LOAD(r0, w0, k0, a0, b0, v0, 0);
; #pragma unroll
;                 for (int t = 0; t < SC_T; t += 2) {
;                     SC_LOAD(r1, w1, k1, a1, b1, v1, t + 1);
;                     SC_STEP(r0, w0, k0, a0, b0, v0, t);
;                     if (t + 2 < SC_T) SC_LOAD(r0, w0, k0, a0, b0, v0, t + 2);
;                     SC_STEP(r1, w1, k1, a1, b1, v1, t + 1);
	v_pk_mul_f32 v[0:1], v[8:9], v[52:53]
	v_pk_mul_f32 v[4:5], v[8:9], v[106:107]
	v_pk_mul_f32 v[2:3], v[10:11], v[54:55]
	v_pk_mul_f32 v[6:7], v[10:11], v[108:109]
	v_pk_fma_f32 v[0:1], v[20:21], v[56:57], v[0:1]
	v_pk_fma_f32 v[4:5], v[20:21], v[110:111], v[4:5]
	v_pk_fma_f32 v[2:3], v[22:23], v[58:59], v[2:3]
	v_pk_fma_f32 v[6:7], v[22:23], v[112:113], v[6:7]
	v_pk_mul_f32 v[12:13], v[8:9], v[36:37]
	v_pk_mul_f32 v[14:15], v[10:11], v[38:39]
	v_pk_add_f32 v[0:1], v[0:1], v[2:3]
	v_pk_add_f32 v[4:5], v[4:5], v[6:7]
	v_pk_mul_f32 v[16:17], v[20:21], v[40:41]
	v_pk_mul_f32 v[18:19], v[22:23], v[42:43]
	v_add_f32_e32 v24, v0, v1
	v_add_f32_e32 v26, v4, v5
	v_pk_fma_f32 v[12:13], v[44:45], v[68:69], v[12:13] op_sel_hi:[1,0,1]
	v_pk_fma_f32 v[14:15], v[46:47], v[68:69], v[14:15] op_sel_hi:[1,0,1]
	v_add_f32_dpp v24, v24, v24 quad_perm:[1,0,3,2] row_mask:0xf bank_mask:0xf bound_ctrl:1
	v_add_f32_dpp v26, v26, v26 quad_perm:[1,0,3,2] row_mask:0xf bank_mask:0xf bound_ctrl:1
	v_pk_fma_f32 v[16:17], v[48:49], v[68:69], v[16:17] op_sel_hi:[1,0,1]
	v_pk_fma_f32 v[18:19], v[50:51], v[68:69], v[18:19] op_sel_hi:[1,0,1]
	v_add_f32_dpp v24, v24, v24 quad_perm:[2,3,0,1] row_mask:0xf bank_mask:0xf bound_ctrl:1
	v_add_f32_dpp v26, v26, v26 quad_perm:[2,3,0,1] row_mask:0xf bank_mask:0xf bound_ctrl:1
	ds_read_b128 v[106:109], v74 offset:4352
	ds_read_b128 v[110:113], v74 offset:4368
	v_add_f32_dpp v24, v24, v24 row_half_mirror row_mask:0xf bank_mask:0xf bound_ctrl:1
	v_add_f32_dpp v26, v26, v26 row_half_mirror row_mask:0xf bank_mask:0xf bound_ctrl:1
	v_pk_fma_f32 v[8:9], v[60:61], v[24:25], v[12:13] op_sel_hi:[1,0,1]
	v_pk_fma_f32 v[10:11], v[62:63], v[24:25], v[14:15] op_sel_hi:[1,0,1]
	v_pk_fma_f32 v[20:21], v[64:65], v[24:25], v[16:17] op_sel_hi:[1,0,1]
	v_pk_fma_f32 v[22:23], v[66:67], v[24:25], v[18:19] op_sel_hi:[1,0,1]
	ds_write_b32 v76, v26 offset:1920
	ds_read_b128 v[52:55], v74 offset:29184
	ds_read_b128 v[56:59], v74 offset:29200
	ds_read_b128 v[36:39], v74 offset:12800
	ds_read_b128 v[40:43], v74 offset:12816
	ds_read_b128 v[44:47], v74 offset:20992
	ds_read_b128 v[48:51], v74 offset:21008
	ds_read_b128 v[60:63], v74 offset:37376
	ds_read_b128 v[64:67], v74 offset:37392
	ds_read_b32 v68, v75 offset:43264
	s_waitcnt lgkmcnt(12)
	v_pk_mul_f32 v[0:1], v[8:9], v[130:131]
	v_pk_mul_f32 v[4:5], v[8:9], v[28:29]
	v_pk_mul_f32 v[2:3], v[10:11], v[132:133]
	v_pk_mul_f32 v[6:7], v[10:11], v[30:31]
	v_pk_fma_f32 v[0:1], v[20:21], v[134:135], v[0:1]
	v_pk_fma_f32 v[4:5], v[20:21], v[32:33], v[4:5]
	v_pk_fma_f32 v[2:3], v[22:23], v[136:137], v[2:3]
	v_pk_fma_f32 v[6:7], v[22:23], v[34:35], v[6:7]
	v_pk_mul_f32 v[12:13], v[8:9], v[114:115]
	v_pk_mul_f32 v[14:15], v[10:11], v[116:117]
	v_pk_add_f32 v[0:1], v[0:1], v[2:3]
	v_pk_add_f32 v[4:5], v[4:5], v[6:7]
	v_pk_mul_f32 v[16:17], v[20:21], v[118:119]
	v_pk_mul_f32 v[18:19], v[22:23], v[120:121]
	v_add_f32_e32 v24, v0, v1
	v_add_f32_e32 v26, v4, v5
	v_pk_fma_f32 v[12:13], v[122:123], v[72:73], v[12:13] op_sel_hi:[1,0,1]
	v_pk_fma_f32 v[14:15], v[124:125], v[72:73], v[14:15] op_sel_hi:[1,0,1]
	v_add_f32_dpp v24, v24, v24 quad_perm:[1,0,3,2] row_mask:0xf bank_mask:0xf bound_ctrl:1
	v_add_f32_dpp v26, v26, v26 quad_perm:[1,0,3,2] row_mask:0xf bank_mask:0xf bound_ctrl:1
	v_pk_fma_f32 v[16:17], v[126:127], v[72:73], v[16:17] op_sel_hi:[1,0,1]
	v_pk_fma_f32 v[18:19], v[128:129], v[72:73], v[18:19] op_sel_hi:[1,0,1]
	v_add_f32_dpp v24, v24, v24 quad_perm:[2,3,0,1] row_mask:0xf bank_mask:0xf bound_ctrl:1
	v_add_f32_dpp v26, v26, v26 quad_perm:[2,3,0,1] row_mask:0xf bank_mask:0xf bound_ctrl:1
	ds_read_b128 v[28:31], v74 offset:4608
	ds_read_b128 v[32:35], v74 offset:4624
	v_add_f32_dpp v24, v24, v24 row_half_mirror row_mask:0xf bank_mask:0xf bound_ctrl:1
	v_add_f32_dpp v26, v26, v26 row_half_mirror row_mask:0xf bank_mask:0xf bound_ctrl:1
	v_pk_fma_f32 v[8:9], v[138:139], v[24:25], v[12:13] op_sel_hi:[1,0,1]
	v_pk_fma_f32 v[10:11], v[140:141], v[24:25], v[14:15] op_sel_hi:[1,0,1]
	v_pk_fma_f32 v[20:21], v[142:143], v[24:25], v[16:17] op_sel_hi:[1,0,1]
	v_pk_fma_f32 v[22:23], v[144:145], v[24:25], v[18:19] op_sel_hi:[1,0,1]
	ds_write_b32 v76, v26 offset:2048
	ds_read_b128 v[130:133], v74 offset:29440
	ds_read_b128 v[134:137], v74 offset:29456
	ds_read_b128 v[114:117], v74 offset:13056
	ds_read_b128 v[118:121], v74 offset:13072
	ds_read_b128 v[122:125], v74 offset:21248
	ds_read_b128 v[126:129], v74 offset:21264
	ds_read_b128 v[138:141], v74 offset:37632
	ds_read_b128 v[142:145], v74 offset:37648
	ds_read_b32 v72, v75 offset:43392
	s_waitcnt lgkmcnt(12)
; __device__ __forceinline__ void rwkv_scan_phase(Frame& F, const bf16* RKV, const float* WAG, const bf16* AGB, const float* k_k, const float* k_a, const float* r_k, bf16* Y, float* BS, float* ST2) {
;     ...
;                 f32x2 r0[4], w0[4], k0[4], a0[4], b0[4], r1[4], w1[4], k1[4], a1[4], b1[4]; float v0, v1;
;                 SC_LOAD(r0, w0, k0, a0, b0, v0, 0);
; #pragma unroll
;                 for (int t = 0; t < SC_T; t += 2) {
;                     SC_LOAD(r1, w1, k1, a1, b1, v1, t + 1);
;                     SC_STEP(r0, w0, k0, a0, b0, v0, t);
;                     if (t + 2 < SC_T) SC_LOAD(r0, w0, k0, a0, b0, v0, t + 2);
;                     SC_STEP(r1, w1, k1, a1, b1, v1, t + 1);
	v_pk_mul_f32 v[0:1], v[8:9], v[52:53]
	v_pk_mul_f32 v[4:5], v[8:9], v[106:107]
	v_pk_mul_f32 v[2:3], v[10:11], v[54:55]
	v_pk_mul_f32 v[6:7], v[10:11], v[108:109]
	v_pk_fma_f32 v[0:1], v[20:21], v[56:57], v[0:1]
	v_pk_fma_f32 v[4:5], v[20:21], v[110:111], v[4:5]
	v_pk_fma_f32 v[2:3], v[22:23], v[58:59], v[2:3]
	v_pk_fma_f32 v[6:7], v[22:23], v[112:113], v[6:7]
	v_pk_mul_f32 v[12:13], v[8:9], v[36:37]
	v_pk_mul_f32 v[14:15], v[10:11], v[38:39]
	v_pk_add_f32 v[0:1], v[0:1], v[2:3]
	v_pk_add_f32 v[4:5], v[4:5], v[6:7]
	v_pk_mul_f32 v[16:17], v[20:21], v[40:41]
	v_pk_mul_f32 v[18:19], v[22:23], v[42:43]
	v_add_f32_e32 v24, v0, v1
	v_add_f32_e32 v26, v4, v5
	v_pk_fma_f32 v[12:13], v[44:45], v[68:69], v[12:13] op_sel_hi:[1,0,1]
	v_pk_fma_f32 v[14:15], v[46:47], v[68:69], v[14:15] op_sel_hi:[1,0,1]
	v_add_f32_dpp v24, v24, v24 quad_perm:[1,0,3,2] row_mask:0xf bank_mask:0xf bound_ctrl:1
	v_add_f32_dpp v26, v26, v26 quad_perm:[1,0,3,2] row_mask:0xf bank_mask:0xf bound_ctrl:1
	v_pk_fma_f32 v[16:17], v[48:49], v[68:69], v[16:17] op_sel_hi:[1,0,1]
	v_pk_fma_f32 v[18:19], v[50:51], v[68:69], v[18:19] op_sel_hi:[1,0,1]
	v_add_f32_dpp v24, v24, v24 quad_perm:[2,3,0,1] row_mask:0xf bank_mask:0xf bound_ctrl:1
	v_add_f32_dpp v26, v26, v26 quad_perm:[2,3,0,1] row_mask:0xf bank_mask:0xf bound_ctrl:1
	ds_read_b128 v[106:109], v74 offset:4864
	ds_read_b128 v[110:113], v74 offset:4880
	v_add_f32_dpp v24, v24, v24 row_half_mirror row_mask:0xf bank_mask:0xf bound_ctrl:1
	v_add_f32_dpp v26, v26, v26 row_half_mirror row_mask:0xf bank_mask:0xf bound_ctrl:1
	v_pk_fma_f32 v[8:9], v[60:61], v[24:25], v[12:13] op_sel_hi:[1,0,1]
	v_pk_fma_f32 v[10:11], v[62:63], v[24:25], v[14:15] op_sel_hi:[1,0,1]
	v_pk_fma_f32 v[20:21], v[64:65], v[24:25], v[16:17] op_sel_hi:[1,0,1]
	v_pk_fma_f32 v[22:23], v[66:67], v[24:25], v[18:19] op_sel_hi:[1,0,1]
	ds_write_b32 v76, v26 offset:2176
	ds_read_b128 v[52:55], v74 offset:29696
	ds_read_b128 v[56:59], v74 offset:29712
	ds_read_b128 v[36:39], v74 offset:13312
	ds_read_b128 v[40:43], v74 offset:13328
	ds_read_b128 v[44:47], v74 offset:21504
	ds_read_b128 v[48:51], v74 offset:21520
	ds_read_b128 v[60:63], v74 offset:37888
	ds_read_b128 v[64:67], v74 offset:37904
	ds_read_b32 v68, v75 offset:43520
	s_waitcnt lgkmcnt(12)
	v_pk_mul_f32 v[0:1], v[8:9], v[130:131]
	v_pk_mul_f32 v[4:5], v[8:9], v[28:29]
	v_pk_mul_f32 v[2:3], v[10:11], v[132:133]
	v_pk_mul_f32 v[6:7], v[10:11], v[30:31]
	v_pk_fma_f32 v[0:1], v[20:21], v[134:135], v[0:1]
	v_pk_fma_f32 v[4:5], v[20:21], v[32:33], v[4:5]
	v_pk_fma_f32 v[2:3], v[22:23], v[136:137], v[2:3]
	v_pk_fma_f32 v[6:7], v[22:23], v[34:35], v[6:7]
	v_pk_mul_f32 v[12:13], v[8:9], v[114:115]
	v_pk_mul_f32 v[14:15], v[10:11], v[116:117]
	v_pk_add_f32 v[0:1], v[0:1], v[2:3]
	v_pk_add_f32 v[4:5], v[4:5], v[6:7]
	v_pk_mul_f32 v[16:17], v[20:21], v[118:119]
	v_pk_mul_f32 v[18:19], v[22:23], v[120:121]
	v_add_f32_e32 v24, v0, v1
	v_add_f32_e32 v26, v4, v5
	v_pk_fma_f32 v[12:13], v[122:123], v[72:73], v[12:13] op_sel_hi:[1,0,1]
	v_pk_fma_f32 v[14:15], v[124:125], v[72:73], v[14:15] op_sel_hi:[1,0,1]
	v_add_f32_dpp v24, v24, v24 quad_perm:[1,0,3,2] row_mask:0xf bank_mask:0xf bound_ctrl:1
	v_add_f32_dpp v26, v26, v26 quad_perm:[1,0,3,2] row_mask:0xf bank_mask:0xf bound_ctrl:1
	v_pk_fma_f32 v[16:17], v[126:127], v[72:73], v[16:17] op_sel_hi:[1,0,1]
	v_pk_fma_f32 v[18:19], v[128:129], v[72:73], v[18:19] op_sel_hi:[1,0,1]
	v_add_f32_dpp v24, v24, v24 quad_perm:[2,3,0,1] row_mask:0xf bank_mask:0xf bound_ctrl:1
	v_add_f32_dpp v26, v26, v26 quad_perm:[2,3,0,1] row_mask:0xf bank_mask:0xf bound_ctrl:1
	ds_read_b128 v[28:31], v74 offset:5120
	ds_read_b128 v[32:35], v74 offset:5136
	v_add_f32_dpp v24, v24, v24 row_half_mirror row_mask:0xf bank_mask:0xf bound_ctrl:1
	v_add_f32_dpp v26, v26, v26 row_half_mirror row_mask:0xf bank_mask:0xf bound_ctrl:1
	v_pk_fma_f32 v[8:9], v[138:139], v[24:25], v[12:13] op_sel_hi:[1,0,1]
	v_pk_fma_f32 v[10:11], v[140:141], v[24:25], v[14:15] op_sel_hi:[1,0,1]
	v_pk_fma_f32 v[20:21], v[142:143], v[24:25], v[16:17] op_sel_hi:[1,0,1]
	v_pk_fma_f32 v[22:23], v[144:145], v[24:25], v[18:19] op_sel_hi:[1,0,1]
	ds_write_b32 v76, v26 offset:2304
	ds_read_b128 v[130:133], v74 offset:29952
	ds_read_b128 v[134:137], v74 offset:29968
	ds_read_b128 v[114:117], v74 offset:13568
	ds_read_b128 v[118:121], v74 offset:13584
	ds_read_b128 v[122:125], v74 offset:21760
	ds_read_b128 v[126:129], v74 offset:21776
	ds_read_b128 v[138:141], v74 offset:38144
	ds_read_b128 v[142:145], v74 offset:38160
	ds_read_b32 v72, v75 offset:43648
	s_waitcnt lgkmcnt(12)
; __device__ __forceinline__ void rwkv_scan_phase(Frame& F, const bf16* RKV, const float* WAG, const bf16* AGB, const float* k_k, const float* k_a, const float* r_k, bf16* Y, float* BS, float* ST2) {
;     ...
;                 f32x2 r0[4], w0[4], k0[4], a0[4], b0[4], r1[4], w1[4], k1[4], a1[4], b1[4]; float v0, v1;
;                 SC_LOAD(r0, w0, k0, a0, b0, v0, 0);
; #pragma unroll
;                 for (int t = 0; t < SC_T; t += 2) {
;                     SC_LOAD(r1, w1, k1, a1, b1, v1, t + 1);
;                     SC_STEP(r0, w0, k0, a0, b0, v0, t);
;                     if (t + 2 < SC_T) SC_LOAD(r0, w0, k0, a0, b0, v0, t + 2);
;                     SC_STEP(r1, w1, k1, a1, b1, v1, t + 1);
	v_pk_mul_f32 v[0:1], v[8:9], v[52:53]
	v_pk_mul_f32 v[4:5], v[8:9], v[106:107]
	v_pk_mul_f32 v[2:3], v[10:11], v[54:55]
	v_pk_mul_f32 v[6:7], v[10:11], v[108:109]
	v_pk_fma_f32 v[0:1], v[20:21], v[56:57], v[0:1]
	v_pk_fma_f32 v[4:5], v[20:21], v[110:111], v[4:5]
	v_pk_fma_f32 v[2:3], v[22:23], v[58:59], v[2:3]
	v_pk_fma_f32 v[6:7], v[22:23], v[112:113], v[6:7]
	v_pk_mul_f32 v[12:13], v[8:9], v[36:37]
	v_pk_mul_f32 v[14:15], v[10:11], v[38:39]
	v_pk_add_f32 v[0:1], v[0:1], v[2:3]
	v_pk_add_f32 v[4:5], v[4:5], v[6:7]
	v_pk_mul_f32 v[16:17], v[20:21], v[40:41]
	v_pk_mul_f32 v[18:19], v[22:23], v[42:43]
	v_add_f32_e32 v24, v0, v1
	v_add_f32_e32 v26, v4, v5
	v_pk_fma_f32 v[12:13], v[44:45], v[68:69], v[12:13] op_sel_hi:[1,0,1]
	v_pk_fma_f32 v[14:15], v[46:47], v[68:69], v[14:15] op_sel_hi:[1,0,1]
	v_add_f32_dpp v24, v24, v24 quad_perm:[1,0,3,2] row_mask:0xf bank_mask:0xf bound_ctrl:1
	v_add_f32_dpp v26, v26, v26 quad_perm:[1,0,3,2] row_mask:0xf bank_mask:0xf bound_ctrl:1
	v_pk_fma_f32 v[16:17], v[48:49], v[68:69], v[16:17] op_sel_hi:[1,0,1]
	v_pk_fma_f32 v[18:19], v[50:51], v[68:69], v[18:19] op_sel_hi:[1,0,1]
	v_add_f32_dpp v24, v24, v24 quad_perm:[2,3,0,1] row_mask:0xf bank_mask:0xf bound_ctrl:1
	v_add_f32_dpp v26, v26, v26 quad_perm:[2,3,0,1] row_mask:0xf bank_mask:0xf bound_ctrl:1
	ds_read_b128 v[106:109], v74 offset:5376
	ds_read_b128 v[110:113], v74 offset:5392
	v_add_f32_dpp v24, v24, v24 row_half_mirror row_mask:0xf bank_mask:0xf bound_ctrl:1
	v_add_f32_dpp v26, v26, v26 row_half_mirror row_mask:0xf bank_mask:0xf bound_ctrl:1
	v_pk_fma_f32 v[8:9], v[60:61], v[24:25], v[12:13] op_sel_hi:[1,0,1]
	v_pk_fma_f32 v[10:11], v[62:63], v[24:25], v[14:15] op_sel_hi:[1,0,1]
	v_pk_fma_f32 v[20:21], v[64:65], v[24:25], v[16:17] op_sel_hi:[1,0,1]
	v_pk_fma_f32 v[22:23], v[66:67], v[24:25], v[18:19] op_sel_hi:[1,0,1]
	ds_write_b32 v76, v26 offset:2432
	ds_read_b128 v[52:55], v74 offset:30208
	ds_read_b128 v[56:59], v74 offset:30224
	ds_read_b128 v[36:39], v74 offset:13824
	ds_read_b128 v[40:43], v74 offset:13840
	ds_read_b128 v[44:47], v74 offset:22016
	ds_read_b128 v[48:51], v74 offset:22032
	ds_read_b128 v[60:63], v74 offset:38400
	ds_read_b128 v[64:67], v74 offset:38416
	ds_read_b32 v68, v75 offset:43776
	s_waitcnt lgkmcnt(12)
	v_pk_mul_f32 v[0:1], v[8:9], v[130:131]
	v_pk_mul_f32 v[4:5], v[8:9], v[28:29]
	v_pk_mul_f32 v[2:3], v[10:11], v[132:133]
	v_pk_mul_f32 v[6:7], v[10:11], v[30:31]
	v_pk_fma_f32 v[0:1], v[20:21], v[134:135], v[0:1]
	v_pk_fma_f32 v[4:5], v[20:21], v[32:33], v[4:5]
	v_pk_fma_f32 v[2:3], v[22:23], v[136:137], v[2:3]
	v_pk_fma_f32 v[6:7], v[22:23], v[34:35], v[6:7]
	v_pk_mul_f32 v[12:13], v[8:9], v[114:115]
	v_pk_mul_f32 v[14:15], v[10:11], v[116:117]
	v_pk_add_f32 v[0:1], v[0:1], v[2:3]
	v_pk_add_f32 v[4:5], v[4:5], v[6:7]
	v_pk_mul_f32 v[16:17], v[20:21], v[118:119]
	v_pk_mul_f32 v[18:19], v[22:23], v[120:121]
	v_add_f32_e32 v24, v0, v1
	v_add_f32_e32 v26, v4, v5
	v_pk_fma_f32 v[12:13], v[122:123], v[72:73], v[12:13] op_sel_hi:[1,0,1]
	v_pk_fma_f32 v[14:15], v[124:125], v[72:73], v[14:15] op_sel_hi:[1,0,1]
	v_add_f32_dpp v24, v24, v24 quad_perm:[1,0,3,2] row_mask:0xf bank_mask:0xf bound_ctrl:1
	v_add_f32_dpp v26, v26, v26 quad_perm:[1,0,3,2] row_mask:0xf bank_mask:0xf bound_ctrl:1
	v_pk_fma_f32 v[16:17], v[126:127], v[72:73], v[16:17] op_sel_hi:[1,0,1]
	v_pk_fma_f32 v[18:19], v[128:129], v[72:73], v[18:19] op_sel_hi:[1,0,1]
	v_add_f32_dpp v24, v24, v24 quad_perm:[2,3,0,1] row_mask:0xf bank_mask:0xf bound_ctrl:1
	v_add_f32_dpp v26, v26, v26 quad_perm:[2,3,0,1] row_mask:0xf bank_mask:0xf bound_ctrl:1
	ds_read_b128 v[28:31], v74 offset:5632
	ds_read_b128 v[32:35], v74 offset:5648
	v_add_f32_dpp v24, v24, v24 row_half_mirror row_mask:0xf bank_mask:0xf bound_ctrl:1
	v_add_f32_dpp v26, v26, v26 row_half_mirror row_mask:0xf bank_mask:0xf bound_ctrl:1
	v_pk_fma_f32 v[8:9], v[138:139], v[24:25], v[12:13] op_sel_hi:[1,0,1]
	v_pk_fma_f32 v[10:11], v[140:141], v[24:25], v[14:15] op_sel_hi:[1,0,1]
	v_pk_fma_f32 v[20:21], v[142:143], v[24:25], v[16:17] op_sel_hi:[1,0,1]
	v_pk_fma_f32 v[22:23], v[144:145], v[24:25], v[18:19] op_sel_hi:[1,0,1]
	ds_write_b32 v76, v26 offset:2560
	ds_read_b128 v[130:133], v74 offset:30464
	ds_read_b128 v[134:137], v74 offset:30480
	ds_read_b128 v[114:117], v74 offset:14080
	ds_read_b128 v[118:121], v74 offset:14096
	ds_read_b128 v[122:125], v74 offset:22272
	ds_read_b128 v[126:129], v74 offset:22288
	ds_read_b128 v[138:141], v74 offset:38656
	ds_read_b128 v[142:145], v74 offset:38672
	ds_read_b32 v72, v75 offset:43904
	s_waitcnt lgkmcnt(12)
; __device__ __forceinline__ void rwkv_scan_phase(Frame& F, const bf16* RKV, const float* WAG, const bf16* AGB, const float* k_k, const float* k_a, const float* r_k, bf16* Y, float* BS, float* ST2) {
;     ...
;                 f32x2 r0[4], w0[4], k0[4], a0[4], b0[4], r1[4], w1[4], k1[4], a1[4], b1[4]; float v0, v1;
;                 SC_LOAD(r0, w0, k0, a0, b0, v0, 0);
; #pragma unroll
;                 for (int t = 0; t < SC_T; t += 2) {
;                     SC_LOAD(r1, w1, k1, a1, b1, v1, t + 1);
;                     SC_STEP(r0, w0, k0, a0, b0, v0, t);
;                     if (t + 2 < SC_T) SC_LOAD(r0, w0, k0, a0, b0, v0, t + 2);
;                     SC_STEP(r1, w1, k1, a1, b1, v1, t + 1);
	v_pk_mul_f32 v[0:1], v[8:9], v[52:53]
	v_pk_mul_f32 v[4:5], v[8:9], v[106:107]
	v_pk_mul_f32 v[2:3], v[10:11], v[54:55]
	v_pk_mul_f32 v[6:7], v[10:11], v[108:109]
	v_pk_fma_f32 v[0:1], v[20:21], v[56:57], v[0:1]
	v_pk_fma_f32 v[4:5], v[20:21], v[110:111], v[4:5]
	v_pk_fma_f32 v[2:3], v[22:23], v[58:59], v[2:3]
	v_pk_fma_f32 v[6:7], v[22:23], v[112:113], v[6:7]
	v_pk_mul_f32 v[12:13], v[8:9], v[36:37]
	v_pk_mul_f32 v[14:15], v[10:11], v[38:39]
	v_pk_add_f32 v[0:1], v[0:1], v[2:3]
	v_pk_add_f32 v[4:5], v[4:5], v[6:7]
	v_pk_mul_f32 v[16:17], v[20:21], v[40:41]
	v_pk_mul_f32 v[18:19], v[22:23], v[42:43]
	v_add_f32_e32 v24, v0, v1
	v_add_f32_e32 v26, v4, v5
	v_pk_fma_f32 v[12:13], v[44:45], v[68:69], v[12:13] op_sel_hi:[1,0,1]
	v_pk_fma_f32 v[14:15], v[46:47], v[68:69], v[14:15] op_sel_hi:[1,0,1]
	v_add_f32_dpp v24, v24, v24 quad_perm:[1,0,3,2] row_mask:0xf bank_mask:0xf bound_ctrl:1
	v_add_f32_dpp v26, v26, v26 quad_perm:[1,0,3,2] row_mask:0xf bank_mask:0xf bound_ctrl:1
	v_pk_fma_f32 v[16:17], v[48:49], v[68:69], v[16:17] op_sel_hi:[1,0,1]
	v_pk_fma_f32 v[18:19], v[50:51], v[68:69], v[18:19] op_sel_hi:[1,0,1]
	v_add_f32_dpp v24, v24, v24 quad_perm:[2,3,0,1] row_mask:0xf bank_mask:0xf bound_ctrl:1
	v_add_f32_dpp v26, v26, v26 quad_perm:[2,3,0,1] row_mask:0xf bank_mask:0xf bound_ctrl:1
	ds_read_b128 v[106:109], v74 offset:5888
	ds_read_b128 v[110:113], v74 offset:5904
	v_add_f32_dpp v24, v24, v24 row_half_mirror row_mask:0xf bank_mask:0xf bound_ctrl:1
	v_add_f32_dpp v26, v26, v26 row_half_mirror row_mask:0xf bank_mask:0xf bound_ctrl:1
	v_pk_fma_f32 v[8:9], v[60:61], v[24:25], v[12:13] op_sel_hi:[1,0,1]
	v_pk_fma_f32 v[10:11], v[62:63], v[24:25], v[14:15] op_sel_hi:[1,0,1]
	v_pk_fma_f32 v[20:21], v[64:65], v[24:25], v[16:17] op_sel_hi:[1,0,1]
	v_pk_fma_f32 v[22:23], v[66:67], v[24:25], v[18:19] op_sel_hi:[1,0,1]
	ds_write_b32 v76, v26 offset:2688
	ds_read_b128 v[52:55], v74 offset:30720
	ds_read_b128 v[56:59], v74 offset:30736
	ds_read_b128 v[36:39], v74 offset:14336
	ds_read_b128 v[40:43], v74 offset:14352
	ds_read_b128 v[44:47], v74 offset:22528
	ds_read_b128 v[48:51], v74 offset:22544
	ds_read_b128 v[60:63], v74 offset:38912
	ds_read_b128 v[64:67], v74 offset:38928
	ds_read_b32 v68, v75 offset:44032
	s_waitcnt lgkmcnt(12)
	v_pk_mul_f32 v[0:1], v[8:9], v[130:131]
	v_pk_mul_f32 v[4:5], v[8:9], v[28:29]
	v_pk_mul_f32 v[2:3], v[10:11], v[132:133]
	v_pk_mul_f32 v[6:7], v[10:11], v[30:31]
	v_pk_fma_f32 v[0:1], v[20:21], v[134:135], v[0:1]
	v_pk_fma_f32 v[4:5], v[20:21], v[32:33], v[4:5]
	v_pk_fma_f32 v[2:3], v[22:23], v[136:137], v[2:3]
	v_pk_fma_f32 v[6:7], v[22:23], v[34:35], v[6:7]
	v_pk_mul_f32 v[12:13], v[8:9], v[114:115]
	v_pk_mul_f32 v[14:15], v[10:11], v[116:117]
	v_pk_add_f32 v[0:1], v[0:1], v[2:3]
	v_pk_add_f32 v[4:5], v[4:5], v[6:7]
	v_pk_mul_f32 v[16:17], v[20:21], v[118:119]
	v_pk_mul_f32 v[18:19], v[22:23], v[120:121]
	v_add_f32_e32 v24, v0, v1
	v_add_f32_e32 v26, v4, v5
	v_pk_fma_f32 v[12:13], v[122:123], v[72:73], v[12:13] op_sel_hi:[1,0,1]
	v_pk_fma_f32 v[14:15], v[124:125], v[72:73], v[14:15] op_sel_hi:[1,0,1]
	v_add_f32_dpp v24, v24, v24 quad_perm:[1,0,3,2] row_mask:0xf bank_mask:0xf bound_ctrl:1
	v_add_f32_dpp v26, v26, v26 quad_perm:[1,0,3,2] row_mask:0xf bank_mask:0xf bound_ctrl:1
	v_pk_fma_f32 v[16:17], v[126:127], v[72:73], v[16:17] op_sel_hi:[1,0,1]
	v_pk_fma_f32 v[18:19], v[128:129], v[72:73], v[18:19] op_sel_hi:[1,0,1]
	v_add_f32_dpp v24, v24, v24 quad_perm:[2,3,0,1] row_mask:0xf bank_mask:0xf bound_ctrl:1
	v_add_f32_dpp v26, v26, v26 quad_perm:[2,3,0,1] row_mask:0xf bank_mask:0xf bound_ctrl:1
	ds_read_b128 v[28:31], v74 offset:6144
	ds_read_b128 v[32:35], v74 offset:6160
	v_add_f32_dpp v24, v24, v24 row_half_mirror row_mask:0xf bank_mask:0xf bound_ctrl:1
	v_add_f32_dpp v26, v26, v26 row_half_mirror row_mask:0xf bank_mask:0xf bound_ctrl:1
	v_pk_fma_f32 v[8:9], v[138:139], v[24:25], v[12:13] op_sel_hi:[1,0,1]
	v_pk_fma_f32 v[10:11], v[140:141], v[24:25], v[14:15] op_sel_hi:[1,0,1]
	v_pk_fma_f32 v[20:21], v[142:143], v[24:25], v[16:17] op_sel_hi:[1,0,1]
	v_pk_fma_f32 v[22:23], v[144:145], v[24:25], v[18:19] op_sel_hi:[1,0,1]
	ds_write_b32 v76, v26 offset:2816
	ds_read_b128 v[130:133], v74 offset:30976
	ds_read_b128 v[134:137], v74 offset:30992
	ds_read_b128 v[114:117], v74 offset:14592
	ds_read_b128 v[118:121], v74 offset:14608
	ds_read_b128 v[122:125], v74 offset:22784
	ds_read_b128 v[126:129], v74 offset:22800
	ds_read_b128 v[138:141], v74 offset:39168
	ds_read_b128 v[142:145], v74 offset:39184
	ds_read_b32 v72, v75 offset:44160
	s_waitcnt lgkmcnt(12)
; __device__ __forceinline__ void rwkv_scan_phase(Frame& F, const bf16* RKV, const float* WAG, const bf16* AGB, const float* k_k, const float* k_a, const float* r_k, bf16* Y, float* BS, float* ST2) {
;     ...
;                 f32x2 r0[4], w0[4], k0[4], a0[4], b0[4], r1[4], w1[4], k1[4], a1[4], b1[4]; float v0, v1;
;                 SC_LOAD(r0, w0, k0, a0, b0, v0, 0);
; #pragma unroll
;                 for (int t = 0; t < SC_T; t += 2) {
;                     SC_LOAD(r1, w1, k1, a1, b1, v1, t + 1);
;                     SC_STEP(r0, w0, k0, a0, b0, v0, t);
;                     if (t + 2 < SC_T) SC_LOAD(r0, w0, k0, a0, b0, v0, t + 2);
;                     SC_STEP(r1, w1, k1, a1, b1, v1, t + 1);
	v_pk_mul_f32 v[0:1], v[8:9], v[52:53]
	v_pk_mul_f32 v[4:5], v[8:9], v[106:107]
	v_pk_mul_f32 v[2:3], v[10:11], v[54:55]
	v_pk_mul_f32 v[6:7], v[10:11], v[108:109]
	v_pk_fma_f32 v[0:1], v[20:21], v[56:57], v[0:1]
	v_pk_fma_f32 v[4:5], v[20:21], v[110:111], v[4:5]
	v_pk_fma_f32 v[2:3], v[22:23], v[58:59], v[2:3]
	v_pk_fma_f32 v[6:7], v[22:23], v[112:113], v[6:7]
	v_pk_mul_f32 v[12:13], v[8:9], v[36:37]
	v_pk_mul_f32 v[14:15], v[10:11], v[38:39]
	v_pk_add_f32 v[0:1], v[0:1], v[2:3]
	v_pk_add_f32 v[4:5], v[4:5], v[6:7]
	v_pk_mul_f32 v[16:17], v[20:21], v[40:41]
	v_pk_mul_f32 v[18:19], v[22:23], v[42:43]
	v_add_f32_e32 v24, v0, v1
	v_add_f32_e32 v26, v4, v5
	v_pk_fma_f32 v[12:13], v[44:45], v[68:69], v[12:13] op_sel_hi:[1,0,1]
	v_pk_fma_f32 v[14:15], v[46:47], v[68:69], v[14:15] op_sel_hi:[1,0,1]
	v_add_f32_dpp v24, v24, v24 quad_perm:[1,0,3,2] row_mask:0xf bank_mask:0xf bound_ctrl:1
	v_add_f32_dpp v26, v26, v26 quad_perm:[1,0,3,2] row_mask:0xf bank_mask:0xf bound_ctrl:1
	v_pk_fma_f32 v[16:17], v[48:49], v[68:69], v[16:17] op_sel_hi:[1,0,1]
	v_pk_fma_f32 v[18:19], v[50:51], v[68:69], v[18:19] op_sel_hi:[1,0,1]
	v_add_f32_dpp v24, v24, v24 quad_perm:[2,3,0,1] row_mask:0xf bank_mask:0xf bound_ctrl:1
	v_add_f32_dpp v26, v26, v26 quad_perm:[2,3,0,1] row_mask:0xf bank_mask:0xf bound_ctrl:1
	ds_read_b128 v[106:109], v74 offset:6400
	ds_read_b128 v[110:113], v74 offset:6416
	v_add_f32_dpp v24, v24, v24 row_half_mirror row_mask:0xf bank_mask:0xf bound_ctrl:1
	v_add_f32_dpp v26, v26, v26 row_half_mirror row_mask:0xf bank_mask:0xf bound_ctrl:1
	v_pk_fma_f32 v[8:9], v[60:61], v[24:25], v[12:13] op_sel_hi:[1,0,1]
	v_pk_fma_f32 v[10:11], v[62:63], v[24:25], v[14:15] op_sel_hi:[1,0,1]
	v_pk_fma_f32 v[20:21], v[64:65], v[24:25], v[16:17] op_sel_hi:[1,0,1]
	v_pk_fma_f32 v[22:23], v[66:67], v[24:25], v[18:19] op_sel_hi:[1,0,1]
	ds_write_b32 v76, v26 offset:2944
	ds_read_b128 v[52:55], v74 offset:31232
	ds_read_b128 v[56:59], v74 offset:31248
	ds_read_b128 v[36:39], v74 offset:14848
	ds_read_b128 v[40:43], v74 offset:14864
	ds_read_b128 v[44:47], v74 offset:23040
	ds_read_b128 v[48:51], v74 offset:23056
	ds_read_b128 v[60:63], v74 offset:39424
	ds_read_b128 v[64:67], v74 offset:39440
	ds_read_b32 v68, v75 offset:44288
	s_waitcnt lgkmcnt(12)
	v_pk_mul_f32 v[0:1], v[8:9], v[130:131]
	v_pk_mul_f32 v[4:5], v[8:9], v[28:29]
	v_pk_mul_f32 v[2:3], v[10:11], v[132:133]
	v_pk_mul_f32 v[6:7], v[10:11], v[30:31]
	v_pk_fma_f32 v[0:1], v[20:21], v[134:135], v[0:1]
	v_pk_fma_f32 v[4:5], v[20:21], v[32:33], v[4:5]
	v_pk_fma_f32 v[2:3], v[22:23], v[136:137], v[2:3]
	v_pk_fma_f32 v[6:7], v[22:23], v[34:35], v[6:7]
	v_pk_mul_f32 v[12:13], v[8:9], v[114:115]
	v_pk_mul_f32 v[14:15], v[10:11], v[116:117]
	v_pk_add_f32 v[0:1], v[0:1], v[2:3]
	v_pk_add_f32 v[4:5], v[4:5], v[6:7]
	v_pk_mul_f32 v[16:17], v[20:21], v[118:119]
	v_pk_mul_f32 v[18:19], v[22:23], v[120:121]
	v_add_f32_e32 v24, v0, v1
	v_add_f32_e32 v26, v4, v5
	v_pk_fma_f32 v[12:13], v[122:123], v[72:73], v[12:13] op_sel_hi:[1,0,1]
	v_pk_fma_f32 v[14:15], v[124:125], v[72:73], v[14:15] op_sel_hi:[1,0,1]
	v_add_f32_dpp v24, v24, v24 quad_perm:[1,0,3,2] row_mask:0xf bank_mask:0xf bound_ctrl:1
	v_add_f32_dpp v26, v26, v26 quad_perm:[1,0,3,2] row_mask:0xf bank_mask:0xf bound_ctrl:1
	v_pk_fma_f32 v[16:17], v[126:127], v[72:73], v[16:17] op_sel_hi:[1,0,1]
	v_pk_fma_f32 v[18:19], v[128:129], v[72:73], v[18:19] op_sel_hi:[1,0,1]
	v_add_f32_dpp v24, v24, v24 quad_perm:[2,3,0,1] row_mask:0xf bank_mask:0xf bound_ctrl:1
	v_add_f32_dpp v26, v26, v26 quad_perm:[2,3,0,1] row_mask:0xf bank_mask:0xf bound_ctrl:1
	ds_read_b128 v[28:31], v74 offset:6656
	ds_read_b128 v[32:35], v74 offset:6672
	v_add_f32_dpp v24, v24, v24 row_half_mirror row_mask:0xf bank_mask:0xf bound_ctrl:1
	v_add_f32_dpp v26, v26, v26 row_half_mirror row_mask:0xf bank_mask:0xf bound_ctrl:1
	v_pk_fma_f32 v[8:9], v[138:139], v[24:25], v[12:13] op_sel_hi:[1,0,1]
	v_pk_fma_f32 v[10:11], v[140:141], v[24:25], v[14:15] op_sel_hi:[1,0,1]
	v_pk_fma_f32 v[20:21], v[142:143], v[24:25], v[16:17] op_sel_hi:[1,0,1]
	v_pk_fma_f32 v[22:23], v[144:145], v[24:25], v[18:19] op_sel_hi:[1,0,1]
	ds_write_b32 v76, v26 offset:3072
	ds_read_b128 v[130:133], v74 offset:31488
	ds_read_b128 v[134:137], v74 offset:31504
	ds_read_b128 v[114:117], v74 offset:15104
	ds_read_b128 v[118:121], v74 offset:15120
	ds_read_b128 v[122:125], v74 offset:23296
	ds_read_b128 v[126:129], v74 offset:23312
	ds_read_b128 v[138:141], v74 offset:39680
	ds_read_b128 v[142:145], v74 offset:39696
	ds_read_b32 v72, v75 offset:44416
	s_waitcnt lgkmcnt(12)
; __device__ __forceinline__ void rwkv_scan_phase(Frame& F, const bf16* RKV, const float* WAG, const bf16* AGB, const float* k_k, const float* k_a, const float* r_k, bf16* Y, float* BS, float* ST2) {
;     ...
;                 f32x2 r0[4], w0[4], k0[4], a0[4], b0[4], r1[4], w1[4], k1[4], a1[4], b1[4]; float v0, v1;
;                 SC_LOAD(r0, w0, k0, a0, b0, v0, 0);
; #pragma unroll
;                 for (int t = 0; t < SC_T; t += 2) {
;                     SC_LOAD(r1, w1, k1, a1, b1, v1, t + 1);
;                     SC_STEP(r0, w0, k0, a0, b0, v0, t);
;                     if (t + 2 < SC_T) SC_LOAD(r0, w0, k0, a0, b0, v0, t + 2);
;                     SC_STEP(r1, w1, k1, a1, b1, v1, t + 1);
	v_pk_mul_f32 v[0:1], v[8:9], v[52:53]
	v_pk_mul_f32 v[4:5], v[8:9], v[106:107]
	v_pk_mul_f32 v[2:3], v[10:11], v[54:55]
	v_pk_mul_f32 v[6:7], v[10:11], v[108:109]
	v_pk_fma_f32 v[0:1], v[20:21], v[56:57], v[0:1]
	v_pk_fma_f32 v[4:5], v[20:21], v[110:111], v[4:5]
	v_pk_fma_f32 v[2:3], v[22:23], v[58:59], v[2:3]
	v_pk_fma_f32 v[6:7], v[22:23], v[112:113], v[6:7]
	v_pk_mul_f32 v[12:13], v[8:9], v[36:37]
	v_pk_mul_f32 v[14:15], v[10:11], v[38:39]
	v_pk_add_f32 v[0:1], v[0:1], v[2:3]
	v_pk_add_f32 v[4:5], v[4:5], v[6:7]
	v_pk_mul_f32 v[16:17], v[20:21], v[40:41]
	v_pk_mul_f32 v[18:19], v[22:23], v[42:43]
	v_add_f32_e32 v24, v0, v1
	v_add_f32_e32 v26, v4, v5
	v_pk_fma_f32 v[12:13], v[44:45], v[68:69], v[12:13] op_sel_hi:[1,0,1]
	v_pk_fma_f32 v[14:15], v[46:47], v[68:69], v[14:15] op_sel_hi:[1,0,1]
	v_add_f32_dpp v24, v24, v24 quad_perm:[1,0,3,2] row_mask:0xf bank_mask:0xf bound_ctrl:1
	v_add_f32_dpp v26, v26, v26 quad_perm:[1,0,3,2] row_mask:0xf bank_mask:0xf bound_ctrl:1
	v_pk_fma_f32 v[16:17], v[48:49], v[68:69], v[16:17] op_sel_hi:[1,0,1]
	v_pk_fma_f32 v[18:19], v[50:51], v[68:69], v[18:19] op_sel_hi:[1,0,1]
	v_add_f32_dpp v24, v24, v24 quad_perm:[2,3,0,1] row_mask:0xf bank_mask:0xf bound_ctrl:1
	v_add_f32_dpp v26, v26, v26 quad_perm:[2,3,0,1] row_mask:0xf bank_mask:0xf bound_ctrl:1
	ds_read_b128 v[106:109], v74 offset:6912
	ds_read_b128 v[110:113], v74 offset:6928
	v_add_f32_dpp v24, v24, v24 row_half_mirror row_mask:0xf bank_mask:0xf bound_ctrl:1
	v_add_f32_dpp v26, v26, v26 row_half_mirror row_mask:0xf bank_mask:0xf bound_ctrl:1
	v_pk_fma_f32 v[8:9], v[60:61], v[24:25], v[12:13] op_sel_hi:[1,0,1]
	v_pk_fma_f32 v[10:11], v[62:63], v[24:25], v[14:15] op_sel_hi:[1,0,1]
	v_pk_fma_f32 v[20:21], v[64:65], v[24:25], v[16:17] op_sel_hi:[1,0,1]
	v_pk_fma_f32 v[22:23], v[66:67], v[24:25], v[18:19] op_sel_hi:[1,0,1]
	ds_write_b32 v76, v26 offset:3200
	ds_read_b128 v[52:55], v74 offset:31744
	ds_read_b128 v[56:59], v74 offset:31760
	ds_read_b128 v[36:39], v74 offset:15360
	ds_read_b128 v[40:43], v74 offset:15376
	ds_read_b128 v[44:47], v74 offset:23552
	ds_read_b128 v[48:51], v74 offset:23568
	ds_read_b128 v[60:63], v74 offset:39936
	ds_read_b128 v[64:67], v74 offset:39952
	ds_read_b32 v68, v75 offset:44544
	s_waitcnt lgkmcnt(12)
	v_pk_mul_f32 v[0:1], v[8:9], v[130:131]
	v_pk_mul_f32 v[4:5], v[8:9], v[28:29]
	v_pk_mul_f32 v[2:3], v[10:11], v[132:133]
	v_pk_mul_f32 v[6:7], v[10:11], v[30:31]
	v_pk_fma_f32 v[0:1], v[20:21], v[134:135], v[0:1]
	v_pk_fma_f32 v[4:5], v[20:21], v[32:33], v[4:5]
	v_pk_fma_f32 v[2:3], v[22:23], v[136:137], v[2:3]
	v_pk_fma_f32 v[6:7], v[22:23], v[34:35], v[6:7]
	v_pk_mul_f32 v[12:13], v[8:9], v[114:115]
	v_pk_mul_f32 v[14:15], v[10:11], v[116:117]
	v_pk_add_f32 v[0:1], v[0:1], v[2:3]
	v_pk_add_f32 v[4:5], v[4:5], v[6:7]
	v_pk_mul_f32 v[16:17], v[20:21], v[118:119]
	v_pk_mul_f32 v[18:19], v[22:23], v[120:121]
	v_add_f32_e32 v24, v0, v1
	v_add_f32_e32 v26, v4, v5
	v_pk_fma_f32 v[12:13], v[122:123], v[72:73], v[12:13] op_sel_hi:[1,0,1]
	v_pk_fma_f32 v[14:15], v[124:125], v[72:73], v[14:15] op_sel_hi:[1,0,1]
	v_add_f32_dpp v24, v24, v24 quad_perm:[1,0,3,2] row_mask:0xf bank_mask:0xf bound_ctrl:1
	v_add_f32_dpp v26, v26, v26 quad_perm:[1,0,3,2] row_mask:0xf bank_mask:0xf bound_ctrl:1
	v_pk_fma_f32 v[16:17], v[126:127], v[72:73], v[16:17] op_sel_hi:[1,0,1]
	v_pk_fma_f32 v[18:19], v[128:129], v[72:73], v[18:19] op_sel_hi:[1,0,1]
	v_add_f32_dpp v24, v24, v24 quad_perm:[2,3,0,1] row_mask:0xf bank_mask:0xf bound_ctrl:1
	v_add_f32_dpp v26, v26, v26 quad_perm:[2,3,0,1] row_mask:0xf bank_mask:0xf bound_ctrl:1
	ds_read_b128 v[28:31], v74 offset:7168
	ds_read_b128 v[32:35], v74 offset:7184
	v_add_f32_dpp v24, v24, v24 row_half_mirror row_mask:0xf bank_mask:0xf bound_ctrl:1
	v_add_f32_dpp v26, v26, v26 row_half_mirror row_mask:0xf bank_mask:0xf bound_ctrl:1
	v_pk_fma_f32 v[8:9], v[138:139], v[24:25], v[12:13] op_sel_hi:[1,0,1]
	v_pk_fma_f32 v[10:11], v[140:141], v[24:25], v[14:15] op_sel_hi:[1,0,1]
	v_pk_fma_f32 v[20:21], v[142:143], v[24:25], v[16:17] op_sel_hi:[1,0,1]
	v_pk_fma_f32 v[22:23], v[144:145], v[24:25], v[18:19] op_sel_hi:[1,0,1]
	ds_write_b32 v76, v26 offset:3328
	ds_read_b128 v[130:133], v74 offset:32000
	ds_read_b128 v[134:137], v74 offset:32016
	ds_read_b128 v[114:117], v74 offset:15616
	ds_read_b128 v[118:121], v74 offset:15632
	ds_read_b128 v[122:125], v74 offset:23808
	ds_read_b128 v[126:129], v74 offset:23824
	ds_read_b128 v[138:141], v74 offset:40192
	ds_read_b128 v[142:145], v74 offset:40208
	ds_read_b32 v72, v75 offset:44672
	s_waitcnt lgkmcnt(12)
; __device__ __forceinline__ void rwkv_scan_phase(Frame& F, const bf16* RKV, const float* WAG, const bf16* AGB, const float* k_k, const float* k_a, const float* r_k, bf16* Y, float* BS, float* ST2) {
;     ...
;                 f32x2 r0[4], w0[4], k0[4], a0[4], b0[4], r1[4], w1[4], k1[4], a1[4], b1[4]; float v0, v1;
;                 SC_LOAD(r0, w0, k0, a0, b0, v0, 0);
; #pragma unroll
;                 for (int t = 0; t < SC_T; t += 2) {
;                     SC_LOAD(r1, w1, k1, a1, b1, v1, t + 1);
;                     SC_STEP(r0, w0, k0, a0, b0, v0, t);
;                     if (t + 2 < SC_T) SC_LOAD(r0, w0, k0, a0, b0, v0, t + 2);
;                     SC_STEP(r1, w1, k1, a1, b1, v1, t + 1);
	v_pk_mul_f32 v[0:1], v[8:9], v[52:53]
	v_pk_mul_f32 v[4:5], v[8:9], v[106:107]
	v_pk_mul_f32 v[2:3], v[10:11], v[54:55]
	v_pk_mul_f32 v[6:7], v[10:11], v[108:109]
	v_pk_fma_f32 v[0:1], v[20:21], v[56:57], v[0:1]
	v_pk_fma_f32 v[4:5], v[20:21], v[110:111], v[4:5]
	v_pk_fma_f32 v[2:3], v[22:23], v[58:59], v[2:3]
	v_pk_fma_f32 v[6:7], v[22:23], v[112:113], v[6:7]
	v_pk_mul_f32 v[12:13], v[8:9], v[36:37]
	v_pk_mul_f32 v[14:15], v[10:11], v[38:39]
	v_pk_add_f32 v[0:1], v[0:1], v[2:3]
	v_pk_add_f32 v[4:5], v[4:5], v[6:7]
	v_pk_mul_f32 v[16:17], v[20:21], v[40:41]
	v_pk_mul_f32 v[18:19], v[22:23], v[42:43]
	v_add_f32_e32 v24, v0, v1
	v_add_f32_e32 v26, v4, v5
	v_pk_fma_f32 v[12:13], v[44:45], v[68:69], v[12:13] op_sel_hi:[1,0,1]
	v_pk_fma_f32 v[14:15], v[46:47], v[68:69], v[14:15] op_sel_hi:[1,0,1]
	v_add_f32_dpp v24, v24, v24 quad_perm:[1,0,3,2] row_mask:0xf bank_mask:0xf bound_ctrl:1
	v_add_f32_dpp v26, v26, v26 quad_perm:[1,0,3,2] row_mask:0xf bank_mask:0xf bound_ctrl:1
	v_pk_fma_f32 v[16:17], v[48:49], v[68:69], v[16:17] op_sel_hi:[1,0,1]
	v_pk_fma_f32 v[18:19], v[50:51], v[68:69], v[18:19] op_sel_hi:[1,0,1]
	v_add_f32_dpp v24, v24, v24 quad_perm:[2,3,0,1] row_mask:0xf bank_mask:0xf bound_ctrl:1
	v_add_f32_dpp v26, v26, v26 quad_perm:[2,3,0,1] row_mask:0xf bank_mask:0xf bound_ctrl:1
	ds_read_b128 v[106:109], v74 offset:7424
	ds_read_b128 v[110:113], v74 offset:7440
	v_add_f32_dpp v24, v24, v24 row_half_mirror row_mask:0xf bank_mask:0xf bound_ctrl:1
	v_add_f32_dpp v26, v26, v26 row_half_mirror row_mask:0xf bank_mask:0xf bound_ctrl:1
	v_pk_fma_f32 v[8:9], v[60:61], v[24:25], v[12:13] op_sel_hi:[1,0,1]
	v_pk_fma_f32 v[10:11], v[62:63], v[24:25], v[14:15] op_sel_hi:[1,0,1]
	v_pk_fma_f32 v[20:21], v[64:65], v[24:25], v[16:17] op_sel_hi:[1,0,1]
	v_pk_fma_f32 v[22:23], v[66:67], v[24:25], v[18:19] op_sel_hi:[1,0,1]
	ds_write_b32 v76, v26 offset:3456
	ds_read_b128 v[52:55], v74 offset:32256
	ds_read_b128 v[56:59], v74 offset:32272
	ds_read_b128 v[36:39], v74 offset:15872
	ds_read_b128 v[40:43], v74 offset:15888
	ds_read_b128 v[44:47], v74 offset:24064
	ds_read_b128 v[48:51], v74 offset:24080
	ds_read_b128 v[60:63], v74 offset:40448
	ds_read_b128 v[64:67], v74 offset:40464
	ds_read_b32 v68, v75 offset:44800
	s_waitcnt lgkmcnt(12)
	v_pk_mul_f32 v[0:1], v[8:9], v[130:131]
	v_pk_mul_f32 v[4:5], v[8:9], v[28:29]
	v_pk_mul_f32 v[2:3], v[10:11], v[132:133]
	v_pk_mul_f32 v[6:7], v[10:11], v[30:31]
	v_pk_fma_f32 v[0:1], v[20:21], v[134:135], v[0:1]
	v_pk_fma_f32 v[4:5], v[20:21], v[32:33], v[4:5]
	v_pk_fma_f32 v[2:3], v[22:23], v[136:137], v[2:3]
	v_pk_fma_f32 v[6:7], v[22:23], v[34:35], v[6:7]
	v_pk_mul_f32 v[12:13], v[8:9], v[114:115]
	v_pk_mul_f32 v[14:15], v[10:11], v[116:117]
	v_pk_add_f32 v[0:1], v[0:1], v[2:3]
	v_pk_add_f32 v[4:5], v[4:5], v[6:7]
	v_pk_mul_f32 v[16:17], v[20:21], v[118:119]
	v_pk_mul_f32 v[18:19], v[22:23], v[120:121]
	v_add_f32_e32 v24, v0, v1
	v_add_f32_e32 v26, v4, v5
	v_pk_fma_f32 v[12:13], v[122:123], v[72:73], v[12:13] op_sel_hi:[1,0,1]
	v_pk_fma_f32 v[14:15], v[124:125], v[72:73], v[14:15] op_sel_hi:[1,0,1]
	v_add_f32_dpp v24, v24, v24 quad_perm:[1,0,3,2] row_mask:0xf bank_mask:0xf bound_ctrl:1
	v_add_f32_dpp v26, v26, v26 quad_perm:[1,0,3,2] row_mask:0xf bank_mask:0xf bound_ctrl:1
	v_pk_fma_f32 v[16:17], v[126:127], v[72:73], v[16:17] op_sel_hi:[1,0,1]
	v_pk_fma_f32 v[18:19], v[128:129], v[72:73], v[18:19] op_sel_hi:[1,0,1]
	v_add_f32_dpp v24, v24, v24 quad_perm:[2,3,0,1] row_mask:0xf bank_mask:0xf bound_ctrl:1
	v_add_f32_dpp v26, v26, v26 quad_perm:[2,3,0,1] row_mask:0xf bank_mask:0xf bound_ctrl:1
	ds_read_b128 v[28:31], v74 offset:7680
	ds_read_b128 v[32:35], v74 offset:7696
	v_add_f32_dpp v24, v24, v24 row_half_mirror row_mask:0xf bank_mask:0xf bound_ctrl:1
	v_add_f32_dpp v26, v26, v26 row_half_mirror row_mask:0xf bank_mask:0xf bound_ctrl:1
	v_pk_fma_f32 v[8:9], v[138:139], v[24:25], v[12:13] op_sel_hi:[1,0,1]
	v_pk_fma_f32 v[10:11], v[140:141], v[24:25], v[14:15] op_sel_hi:[1,0,1]
	v_pk_fma_f32 v[20:21], v[142:143], v[24:25], v[16:17] op_sel_hi:[1,0,1]
	v_pk_fma_f32 v[22:23], v[144:145], v[24:25], v[18:19] op_sel_hi:[1,0,1]
	ds_write_b32 v76, v26 offset:3584
	ds_read_b128 v[130:133], v74 offset:32512
	ds_read_b128 v[134:137], v74 offset:32528
	ds_read_b128 v[114:117], v74 offset:16128
	ds_read_b128 v[118:121], v74 offset:16144
	ds_read_b128 v[122:125], v74 offset:24320
	ds_read_b128 v[126:129], v74 offset:24336
	ds_read_b128 v[138:141], v74 offset:40704
	ds_read_b128 v[142:145], v74 offset:40720
	ds_read_b32 v72, v75 offset:44928
	s_waitcnt lgkmcnt(12)
; __device__ __forceinline__ void rwkv_scan_phase(Frame& F, const bf16* RKV, const float* WAG, const bf16* AGB, const float* k_k, const float* k_a, const float* r_k, bf16* Y, float* BS, float* ST2) {
;     ...
;                 f32x2 r0[4], w0[4], k0[4], a0[4], b0[4], r1[4], w1[4], k1[4], a1[4], b1[4]; float v0, v1;
;                 SC_LOAD(r0, w0, k0, a0, b0, v0, 0);
; #pragma unroll
;                 for (int t = 0; t < SC_T; t += 2) {
;                     SC_LOAD(r1, w1, k1, a1, b1, v1, t + 1);
;                     SC_STEP(r0, w0, k0, a0, b0, v0, t);
;                     if (t + 2 < SC_T) SC_LOAD(r0, w0, k0, a0, b0, v0, t + 2);
;                     SC_STEP(r1, w1, k1, a1, b1, v1, t + 1);
;                 }
;     ...
;                 __syncthreads();
	v_pk_mul_f32 v[0:1], v[8:9], v[52:53]
	v_pk_mul_f32 v[4:5], v[8:9], v[106:107]
	v_pk_mul_f32 v[2:3], v[10:11], v[54:55]
	v_pk_mul_f32 v[6:7], v[10:11], v[108:109]
	v_pk_fma_f32 v[0:1], v[20:21], v[56:57], v[0:1]
	v_pk_fma_f32 v[4:5], v[20:21], v[110:111], v[4:5]
	v_pk_fma_f32 v[2:3], v[22:23], v[58:59], v[2:3]
	v_pk_fma_f32 v[6:7], v[22:23], v[112:113], v[6:7]
	v_pk_mul_f32 v[12:13], v[8:9], v[36:37]
	v_pk_mul_f32 v[14:15], v[10:11], v[38:39]
	v_pk_add_f32 v[0:1], v[0:1], v[2:3]
	v_pk_add_f32 v[4:5], v[4:5], v[6:7]
	v_pk_mul_f32 v[16:17], v[20:21], v[40:41]
	v_pk_mul_f32 v[18:19], v[22:23], v[42:43]
	v_add_f32_e32 v24, v0, v1
	v_add_f32_e32 v26, v4, v5
	v_pk_fma_f32 v[12:13], v[44:45], v[68:69], v[12:13] op_sel_hi:[1,0,1]
	v_pk_fma_f32 v[14:15], v[46:47], v[68:69], v[14:15] op_sel_hi:[1,0,1]
	v_add_f32_dpp v24, v24, v24 quad_perm:[1,0,3,2] row_mask:0xf bank_mask:0xf bound_ctrl:1
	v_add_f32_dpp v26, v26, v26 quad_perm:[1,0,3,2] row_mask:0xf bank_mask:0xf bound_ctrl:1
	v_pk_fma_f32 v[16:17], v[48:49], v[68:69], v[16:17] op_sel_hi:[1,0,1]
	v_pk_fma_f32 v[18:19], v[50:51], v[68:69], v[18:19] op_sel_hi:[1,0,1]
	v_add_f32_dpp v24, v24, v24 quad_perm:[2,3,0,1] row_mask:0xf bank_mask:0xf bound_ctrl:1
	v_add_f32_dpp v26, v26, v26 quad_perm:[2,3,0,1] row_mask:0xf bank_mask:0xf bound_ctrl:1
	ds_read_b128 v[106:109], v74 offset:7936
	ds_read_b128 v[110:113], v74 offset:7952
	v_add_f32_dpp v24, v24, v24 row_half_mirror row_mask:0xf bank_mask:0xf bound_ctrl:1
	v_add_f32_dpp v26, v26, v26 row_half_mirror row_mask:0xf bank_mask:0xf bound_ctrl:1
	v_pk_fma_f32 v[8:9], v[60:61], v[24:25], v[12:13] op_sel_hi:[1,0,1]
	v_pk_fma_f32 v[10:11], v[62:63], v[24:25], v[14:15] op_sel_hi:[1,0,1]
	v_pk_fma_f32 v[20:21], v[64:65], v[24:25], v[16:17] op_sel_hi:[1,0,1]
	v_pk_fma_f32 v[22:23], v[66:67], v[24:25], v[18:19] op_sel_hi:[1,0,1]
	ds_write_b32 v76, v26 offset:3712
	s_waitcnt lgkmcnt(3)
	v_pk_mul_f32 v[0:1], v[8:9], v[130:131]
	v_pk_mul_f32 v[4:5], v[8:9], v[28:29]
	v_pk_mul_f32 v[2:3], v[10:11], v[132:133]
	v_pk_mul_f32 v[6:7], v[10:11], v[30:31]
	v_pk_fma_f32 v[0:1], v[20:21], v[134:135], v[0:1]
	v_pk_fma_f32 v[4:5], v[20:21], v[32:33], v[4:5]
	v_pk_fma_f32 v[2:3], v[22:23], v[136:137], v[2:3]
	v_pk_fma_f32 v[6:7], v[22:23], v[34:35], v[6:7]
	v_pk_mul_f32 v[12:13], v[8:9], v[114:115]
	v_pk_mul_f32 v[14:15], v[10:11], v[116:117]
	v_pk_add_f32 v[0:1], v[0:1], v[2:3]
	v_pk_add_f32 v[4:5], v[4:5], v[6:7]
	v_pk_mul_f32 v[16:17], v[20:21], v[118:119]
	v_pk_mul_f32 v[18:19], v[22:23], v[120:121]
	v_add_f32_e32 v24, v0, v1
	v_add_f32_e32 v26, v4, v5
	v_pk_fma_f32 v[12:13], v[122:123], v[72:73], v[12:13] op_sel_hi:[1,0,1]
	v_pk_fma_f32 v[14:15], v[124:125], v[72:73], v[14:15] op_sel_hi:[1,0,1]
	v_add_f32_dpp v24, v24, v24 quad_perm:[1,0,3,2] row_mask:0xf bank_mask:0xf bound_ctrl:1
	v_add_f32_dpp v26, v26, v26 quad_perm:[1,0,3,2] row_mask:0xf bank_mask:0xf bound_ctrl:1
	v_pk_fma_f32 v[16:17], v[126:127], v[72:73], v[16:17] op_sel_hi:[1,0,1]
	v_pk_fma_f32 v[18:19], v[128:129], v[72:73], v[18:19] op_sel_hi:[1,0,1]
	v_add_f32_dpp v24, v24, v24 quad_perm:[2,3,0,1] row_mask:0xf bank_mask:0xf bound_ctrl:1
	v_add_f32_dpp v26, v26, v26 quad_perm:[2,3,0,1] row_mask:0xf bank_mask:0xf bound_ctrl:1
	s_nop 0
	v_add_f32_dpp v24, v24, v24 row_half_mirror row_mask:0xf bank_mask:0xf bound_ctrl:1
	v_add_f32_dpp v26, v26, v26 row_half_mirror row_mask:0xf bank_mask:0xf bound_ctrl:1
	v_pk_fma_f32 v[8:9], v[138:139], v[24:25], v[12:13] op_sel_hi:[1,0,1]
	v_pk_fma_f32 v[10:11], v[140:141], v[24:25], v[14:15] op_sel_hi:[1,0,1]
	v_pk_fma_f32 v[20:21], v[142:143], v[24:25], v[16:17] op_sel_hi:[1,0,1]
	v_pk_fma_f32 v[22:23], v[144:145], v[24:25], v[18:19] op_sel_hi:[1,0,1]
	ds_write_b32 v76, v26 offset:3840
	s_waitcnt lgkmcnt(2)
	v_pk_mul_f32 v[4:5], v[8:9], v[106:107]
	v_pk_mul_f32 v[6:7], v[10:11], v[108:109]
	v_pk_fma_f32 v[4:5], v[20:21], v[110:111], v[4:5]
	v_pk_fma_f32 v[6:7], v[22:23], v[112:113], v[6:7]
	v_pk_add_f32 v[4:5], v[4:5], v[6:7]
	v_add_f32_e32 v26, v4, v5
	s_nop 1
	v_add_f32_dpp v26, v26, v26 quad_perm:[1,0,3,2] row_mask:0xf bank_mask:0xf bound_ctrl:1
	s_nop 1
	v_add_f32_dpp v26, v26, v26 quad_perm:[2,3,0,1] row_mask:0xf bank_mask:0xf bound_ctrl:1
	s_nop 1
	v_add_f32_dpp v26, v26, v26 row_half_mirror row_mask:0xf bank_mask:0xf bound_ctrl:1
	ds_write_b32 v76, v26 offset:3968
	s_mov_b64 s[6:7], 0
	s_branch .LBB0_1691
